# code placement: GQA loop and OUT/DOWN full k-loops moved from byte phase 4 to phase 0 (mod 8) with one s_nop 0 before each and a compensating one after, all other code at unchanged offsets
# speedup vs baseline: 1.0120x; 1.0007x over previous
.LBB0_753:
	s_and_b64 vcc, exec, s[0:1]
	s_cbranch_vccz .LBB0_757
	s_waitcnt vmcnt(18)
	v_mov_b32_e32 v22, v179
	v_mov_b64_e32 v[8:9], s[66:67]
	v_and_b32_e32 v105, 31, v22
	v_ashrrev_i32_e32 v0, 1, v22
	v_and_b32_e32 v0, 0xffffffe0, v0
	v_or_b32_e32 v1, s4, v105
	v_add_u32_e32 v0, v1, v0
	v_bfe_u32 v23, v22, 5, 1
	v_mad_i64_i32 v[0:1], s[0:1], v0, s43, v[8:9]
	s_lshl_b32 s96, s3, 1
	v_lshl_add_u64 v[0:1], v[0:1], 0, s[96:97]
	v_lshlrev_b32_e32 v176, 4, v23
	v_lshl_add_u64 v[0:1], v[0:1], 0, v[176:177]
	v_ashrrev_i32_e32 v107, 3, v22
	s_mov_b32 s7, s95
	global_load_dwordx4 v[76:79], v[0:1], off offset:1536
	global_load_dwordx4 v[72:75], v[0:1], off offset:1568
	global_load_dwordx4 v[68:71], v[0:1], off offset:1600
	global_load_dwordx4 v[64:67], v[0:1], off offset:1632
	v_add_u32_e32 v0, s7, v107
	v_mad_i64_i32 v[0:1], s[0:1], v0, s43, v[8:9]
	s_lshl_b32 s96, s6, 1
	v_lshlrev_b32_e32 v2, 4, v22
	v_lshl_add_u64 v[0:1], v[0:1], 0, s[96:97]
	v_and_b32_e32 v98, 0x70, v2
	v_mov_b32_e32 v99, v177
	v_lshl_add_u64 v[0:1], v[0:1], 0, v[98:99]
	global_load_dwordx4 v[0:3], v[0:1], off
	s_movk_i32 s6, 0x2200
	v_mad_i64_i32 v[4:5], s[0:1], v107, s6, v[96:97]
	v_lshl_add_u64 v[4:5], v[4:5], 0, v[98:99]
	s_waitcnt vmcnt(20)
	v_add_u32_e32 v24, 0x100, v22
	global_load_dwordx4 v[4:7], v[4:5], off
	v_ashrrev_i32_e32 v108, 3, v24
	v_add_u32_e32 v10, s7, v108
	v_mad_i64_i32 v[8:9], s[0:1], v10, s43, v[8:9]
	v_lshl_add_u64 v[8:9], v[8:9], 0, s[96:97]
	v_lshl_add_u64 v[8:9], v[8:9], 0, v[98:99]
	global_load_dwordx4 v[8:11], v[8:9], off
	v_mad_i64_i32 v[12:13], s[0:1], v108, s6, v[96:97]
	v_lshl_add_u64 v[12:13], v[12:13], 0, v[98:99]
	global_load_dwordx4 v[12:15], v[12:13], off
	v_mad_u64_u32 v[20:21], s[0:1], v107, s42, v[98:99]
	v_mad_i64_i32 v[16:17], s[0:1], v107, s6, 0
	v_mad_i64_i32 v[18:19], s[0:1], v108, s6, 0
	v_or_b32_e32 v16, v16, v98
	v_or_b32_e32 v18, v18, v98
	v_lshlrev_b32_e32 v106, 3, v23
	v_lshlrev_b32_e32 v104, 2, v23
	v_add_u32_e32 v109, 64, v108
	v_add_u32_e32 v110, 64, v107
	s_movk_i32 s8, 0xff00
	s_movk_i32 s9, 0x4800
	s_mov_b64 s[10:11], 0x80
	v_readlane_b32 s12, v255, 5
	s_waitcnt vmcnt(3)
	ds_write_b128 v20, v[0:3]
	v_and_b32_e32 v0, -8, v22
	v_sub_u32_e32 v0, v20, v0
	v_add_u32_e32 v0, 0x4800, v0
	s_waitcnt vmcnt(2)
	ds_write2_b64 v0, v[4:5], v[6:7] offset1:1
	v_mad_u64_u32 v[0:1], s[0:1], v108, s42, v[98:99]
	s_add_u32 s0, s66, s96
	s_addc_u32 s1, s67, 0
	v_lshl_add_u64 v[96:97], s[0:1], 0, v[98:99]
	v_readlane_b32 s0, v255, 6
	v_and_b32_e32 v1, -8, v24
	s_add_i32 s0, s0, s5
	v_readlane_b32 s1, v254, 12
	s_waitcnt vmcnt(1)
	ds_write_b128 v0, v[8:11]
	v_sub_u32_e32 v0, v0, v1
	s_add_u32 s0, s1, s0
	v_readlane_b32 s1, v254, 13
	v_add_u32_e32 v0, 0x4800, v0
	s_addc_u32 s1, s1, 0
	v_mov_b32_e32 v99, 0
	s_waitcnt vmcnt(0)
	ds_write2_b64 v0, v[12:13], v[14:15] offset1:1
	v_lshl_add_u64 v[100:101], s[0:1], 0, v[16:17]
	v_lshl_add_u64 v[102:103], s[0:1], 0, v[18:19]
	s_mov_b32 s0, 0
	s_mov_b32 s5, 0
	v_mov_b32_e32 v0, 0
	v_mov_b32_e32 v1, v99
	v_mov_b32_e32 v2, v99
	v_mov_b32_e32 v3, v99
	v_mov_b32_e32 v4, v99
	v_mov_b32_e32 v5, v99
	v_mov_b32_e32 v6, v99
	v_mov_b32_e32 v7, v99
	v_mov_b32_e32 v8, v99
	v_mov_b32_e32 v9, v99
	v_mov_b32_e32 v10, v99
	v_mov_b32_e32 v11, v99
	v_mov_b32_e32 v12, v99
	v_mov_b32_e32 v13, v99
	v_mov_b32_e32 v14, v99
	v_mov_b32_e32 v15, v99
	v_mov_b32_e32 v16, 0
	v_mov_b32_e32 v17, v99
	v_mov_b32_e32 v18, v99
	v_mov_b32_e32 v19, v99
	v_mov_b32_e32 v20, v99
	v_mov_b32_e32 v21, v99
	v_mov_b32_e32 v22, v99
	v_mov_b32_e32 v23, v99
	v_mov_b32_e32 v24, v99
	v_mov_b32_e32 v25, v99
	v_mov_b32_e32 v26, v99
	v_mov_b32_e32 v27, v99
	v_mov_b32_e32 v28, v99
	v_mov_b32_e32 v29, v99
	v_mov_b32_e32 v30, v99
	v_mov_b32_e32 v31, v99
	s_waitcnt lgkmcnt(0)
	s_barrier
	v_mad_u32_u24 v156, v105, s42, v176
	v_mad_u32_u24 v157, v105, s42, v176
	v_mad_u32_u24 v188, v107, s42, v98
	v_mad_u32_u24 v189, v108, s42, v98
	v_lshrrev_b32_e32 v111, 1, v98
	v_and_b32_e32 v111, 8, v111
	v_sub_u32_e32 v111, v98, v111
	v_mad_u32_u24 v181, v107, s42, v111
	v_mad_u32_u24 v183, v108, s42, v111
	v_add_u32_e32 v157, 0x9000, v157
	v_add_u32_e32 v181, 0x9000, v181
	v_add_u32_e32 v183, 0x9000, v183
	v_mad_u32_u24 v250, v107, s34, v98
	v_mad_u32_u24 v251, v108, s34, v98
	v_add_u32_e32 v250, 0x4800, v250
	v_add_u32_e32 v251, 0x4800, v251
	ds_read2_b64 v[84:87], v250 offset1:1
	ds_read2_b64 v[80:83], v251 offset1:1
	s_waitcnt lgkmcnt(1)
	ds_write2_b64 v181, v[84:85], v[86:87] offset1:2
	s_waitcnt lgkmcnt(1)
	ds_write2_b64 v183, v[80:81], v[82:83] offset1:2
	s_waitcnt lgkmcnt(0)
	s_barrier
	v_mov_b32_e32 v144, 0
	v_mov_b32_e32 v145, 0
	v_mov_b32_e32 v146, 0
	v_mov_b32_e32 v147, 0
	v_mov_b32_e32 v148, 0
	v_mov_b32_e32 v149, 0
	v_mov_b32_e32 v150, 0
	v_mov_b32_e32 v151, 0
	v_mov_b32_e32 v152, 0
	v_mov_b32_e32 v153, 0
	v_mov_b32_e32 v154, 0
	v_mov_b32_e32 v155, 0
	v_mov_b32_e32 v160, 0
	v_mov_b32_e32 v161, 0
	v_mov_b32_e32 v162, 0
	v_mov_b32_e32 v163, 0
	v_mov_b32_e32 v164, 0
	v_mov_b32_e32 v165, 0
	v_mov_b32_e32 v166, 0
	v_mov_b32_e32 v167, 0
	v_mov_b32_e32 v168, 0
	v_mov_b32_e32 v169, 0
	v_mov_b32_e32 v170, 0
	v_mov_b32_e32 v171, 0
	v_mov_b32_e32 v184, 0
	v_mov_b32_e32 v185, 0
	v_mov_b32_e32 v186, 0
	v_mov_b32_e32 v187, 0
	v_mov_b32_e32 v196, 0
	v_mov_b32_e32 v197, 0
	v_mov_b32_e32 v198, 0
	v_mov_b32_e32 v199, 0
	v_mov_b32_e32 v200, 0
	v_mov_b32_e32 v201, 0
	v_mov_b32_e32 v202, 0
	v_mov_b32_e32 v203, 0
	v_mov_b32_e32 v204, 0
	v_mov_b32_e32 v205, 0
	v_mov_b32_e32 v206, 0
	v_mov_b32_e32 v207, 0
	v_mov_b32_e32 v246, 0
	v_mov_b32_e32 v247, 0
	v_mov_b32_e32 v248, 0
	v_mov_b32_e32 v249, 0
	v_mov_b32_e32 v32, 0xc47a0000
	v_mov_b32_e32 v33, 0xc47a0000
	v_mov_b32_e32 v34, 0xc47a0000
	v_mov_b32_e32 v35, 0xc47a0000
	v_mov_b32_e32 v36, 0xc47a0000
	v_mov_b32_e32 v37, 0xc47a0000
	v_mov_b32_e32 v38, 0xc47a0000
	v_mov_b32_e32 v39, 0xc47a0000
	v_mov_b32_e32 v40, 0xc47a0000
	v_mov_b32_e32 v41, 0xc47a0000
	v_mov_b32_e32 v42, 0xc47a0000
	v_mov_b32_e32 v43, 0xc47a0000
	v_mov_b32_e32 v44, 0xc47a0000
	v_mov_b32_e32 v45, 0xc47a0000
	v_mov_b32_e32 v46, 0xc47a0000
	v_mov_b32_e32 v47, 0xc47a0000
	s_nop 0

.Lgq_nostore:
	s_add_i32 s0, s0, 64
	s_add_i32 s5, s5, 1
	s_waitcnt lgkmcnt(0)
	s_barrier
	s_cmpk_lg_i32 s0, 0x1100
	s_cbranch_scc1 .Lgq_top
	s_nop 0
	v_exp_f32_e32 v32, v32
	v_exp_f32_e32 v33, v33
	v_exp_f32_e32 v34, v34
	v_exp_f32_e32 v35, v35
	v_exp_f32_e32 v36, v36
	v_exp_f32_e32 v37, v37
	v_add_f32_e32 v246, v32, v246
	v_add_f32_e32 v247, v33, v247
	v_cvt_pk_bf16_f32 v238, v32, v33
	v_exp_f32_e32 v38, v38
	v_exp_f32_e32 v39, v39
	v_add_f32_e32 v248, v34, v248
	v_add_f32_e32 v249, v35, v249
	v_cvt_pk_bf16_f32 v239, v34, v35
	v_exp_f32_e32 v40, v40
	v_exp_f32_e32 v41, v41
	v_add_f32_e32 v246, v36, v246
	v_add_f32_e32 v247, v37, v247
	v_cvt_pk_bf16_f32 v240, v36, v37
	v_exp_f32_e32 v42, v42
	v_exp_f32_e32 v43, v43
	v_add_f32_e32 v248, v38, v248
	v_add_f32_e32 v249, v39, v249
	v_cvt_pk_bf16_f32 v241, v38, v39
	v_exp_f32_e32 v44, v44
	v_exp_f32_e32 v45, v45
	v_add_f32_e32 v246, v40, v246
	v_add_f32_e32 v247, v41, v247
	v_cvt_pk_bf16_f32 v242, v40, v41
	v_exp_f32_e32 v46, v46
	v_exp_f32_e32 v47, v47
	v_add_f32_e32 v248, v42, v248
	v_add_f32_e32 v249, v43, v249
	v_cvt_pk_bf16_f32 v243, v42, v43
	v_add_f32_e32 v246, v44, v246
	v_add_f32_e32 v247, v45, v247
	v_cvt_pk_bf16_f32 v244, v44, v45
	v_add_f32_e32 v248, v46, v248
	v_add_f32_e32 v249, v47, v249
	v_cvt_pk_bf16_f32 v245, v46, v47
	s_nop 1
	v_mfma_f32_32x32x16_bf16 v[0:15], v[144:147], v[200:203], v[0:15]
	v_mfma_f32_32x32x16_bf16 v[16:31], v[164:167], v[200:203], v[16:31]
	v_mfma_f32_32x32x16_bf16 v[0:15], v[148:151], v[204:207], v[0:15]
	v_mfma_f32_32x32x16_bf16 v[16:31], v[168:171], v[204:207], v[16:31]
	v_mfma_f32_32x32x16_bf16 v[0:15], v[152:155], v[238:241], v[0:15]
	v_mfma_f32_32x32x16_bf16 v[16:31], v[184:187], v[238:241], v[16:31]
	v_mfma_f32_32x32x16_bf16 v[0:15], v[160:163], v[242:245], v[0:15]
	v_mfma_f32_32x32x16_bf16 v[16:31], v[196:199], v[242:245], v[16:31]
	v_add_f32_e32 v246, v246, v247
	v_add_f32_e32 v248, v248, v249
	s_nop 1
	v_add_f32_e32 v246, v246, v248
	s_nop 1
	v_add_f32_e32 v32, v99, v246
	s_nop 7
	s_nop 7
	ds_bpermute_b32 v35, v231, v32
	v_mov_b32_e32 v33, v179
	s_waitcnt lgkmcnt(0)
	s_barrier
	v_add_f32_e32 v32, v32, v35
	v_div_scale_f32 v35, s[0:1], v32, v32, 1.0
	v_rcp_f32_e32 v36, v35
	s_add_i32 s5, s3, 0x100
	v_ashrrev_i32_e32 v34, 1, v33
	v_fma_f32 v37, -v35, v36, 1.0
	v_fmac_f32_e32 v36, v37, v36
	v_div_scale_f32 v37, vcc, 1.0, v32, 1.0
	v_mul_f32_e32 v38, v37, v36
	v_fma_f32 v39, -v35, v38, v37
	v_fmac_f32_e32 v38, v39, v36
	v_add_u32_e32 v34, s4, v34
	v_fma_f32 v35, -v35, v38, v37
	v_div_fmas_f32 v35, v35, v36, v38
	v_ashrrev_i32_e32 v34, 5, v34
	v_div_fixup_f32 v32, v35, v32, 1.0
	v_ashrrev_i32_e32 v35, 31, v34
	v_lshlrev_b64 v[34:35], 16, v[34:35]
	s_lshr_b32 s96, s5, 4
	v_lshl_add_u64 v[34:35], s[64:65], 0, v[34:35]
	v_pk_mul_f32 v[0:1], v[0:1], v[32:33] op_sel_hi:[1,0]
	v_pk_mul_f32 v[2:3], v[2:3], v[32:33] op_sel_hi:[1,0]
	s_lshl_b64 s[0:1], s[96:97], 10
	v_lshlrev_b32_e32 v36, 4, v33
	v_cvt_pk_bf16_f32 v0, v0, v1
	v_cvt_pk_bf16_f32 v1, v2, v3
	v_lshl_add_u64 v[2:3], v[34:35], 0, s[0:1]
	v_and_b32_e32 v176, 0x1f0, v36
	v_lshrrev_b32_e32 v33, 2, v33
	v_lshl_add_u64 v[2:3], v[2:3], 0, v[176:177]
	v_and_b32_e32 v36, 8, v33
	v_mov_b32_e32 v37, v177
	s_add_i32 s0, s3, 0x108
	v_lshl_add_u64 v[2:3], v[2:3], 0, v[36:37]
	s_lshr_b32 s96, s0, 4
	global_store_dwordx2 v[2:3], v[0:1], off
	v_pk_mul_f32 v[0:1], v[4:5], v[32:33] op_sel_hi:[1,0]
	v_pk_mul_f32 v[2:3], v[6:7], v[32:33] op_sel_hi:[1,0]
	s_lshl_b64 s[0:1], s[96:97], 10
	v_cvt_pk_bf16_f32 v0, v0, v1
	v_cvt_pk_bf16_f32 v1, v2, v3
	v_lshl_add_u64 v[2:3], v[34:35], 0, s[0:1]
	v_lshl_add_u64 v[2:3], v[2:3], 0, v[176:177]
	s_add_i32 s0, s3, 0x110
	v_lshl_add_u64 v[2:3], v[2:3], 0, v[36:37]
	s_lshr_b32 s96, s0, 4
	global_store_dwordx2 v[2:3], v[0:1], off offset:512
	v_pk_mul_f32 v[0:1], v[8:9], v[32:33] op_sel_hi:[1,0]
	v_pk_mul_f32 v[2:3], v[10:11], v[32:33] op_sel_hi:[1,0]
	s_lshl_b64 s[0:1], s[96:97], 10
	v_cvt_pk_bf16_f32 v0, v0, v1
	v_cvt_pk_bf16_f32 v1, v2, v3
	v_lshl_add_u64 v[2:3], v[34:35], 0, s[0:1]
	v_lshl_add_u64 v[2:3], v[2:3], 0, v[176:177]
	s_add_i32 s0, s3, 0x118
	v_lshl_add_u64 v[2:3], v[2:3], 0, v[36:37]
	s_lshr_b32 s96, s0, 4
	global_store_dwordx2 v[2:3], v[0:1], off
	v_pk_mul_f32 v[0:1], v[12:13], v[32:33] op_sel_hi:[1,0]
	v_pk_mul_f32 v[2:3], v[14:15], v[32:33] op_sel_hi:[1,0]
	s_lshl_b64 s[0:1], s[96:97], 10
	v_cvt_pk_bf16_f32 v0, v0, v1
	v_cvt_pk_bf16_f32 v1, v2, v3
	v_lshl_add_u64 v[2:3], v[34:35], 0, s[0:1]
	v_lshl_add_u64 v[2:3], v[2:3], 0, v[176:177]
	s_add_i32 s0, s3, 0x120
	v_lshl_add_u64 v[2:3], v[2:3], 0, v[36:37]
	s_lshr_b32 s96, s0, 4
	global_store_dwordx2 v[2:3], v[0:1], off offset:512
	v_pk_mul_f32 v[0:1], v[16:17], v[32:33] op_sel_hi:[1,0]
	v_pk_mul_f32 v[2:3], v[18:19], v[32:33] op_sel_hi:[1,0]
	s_lshl_b64 s[0:1], s[96:97], 10
	v_cvt_pk_bf16_f32 v0, v0, v1
	v_cvt_pk_bf16_f32 v1, v2, v3
	v_lshl_add_u64 v[2:3], v[34:35], 0, s[0:1]
	v_lshl_add_u64 v[2:3], v[2:3], 0, v[176:177]
	s_add_i32 s0, s3, 0x128
	v_lshl_add_u64 v[2:3], v[2:3], 0, v[36:37]
	s_lshr_b32 s96, s0, 4
	global_store_dwordx2 v[2:3], v[0:1], off
	v_pk_mul_f32 v[0:1], v[20:21], v[32:33] op_sel_hi:[1,0]
	v_pk_mul_f32 v[2:3], v[22:23], v[32:33] op_sel_hi:[1,0]
	s_lshl_b64 s[0:1], s[96:97], 10
	v_cvt_pk_bf16_f32 v0, v0, v1
	v_cvt_pk_bf16_f32 v1, v2, v3
	v_lshl_add_u64 v[2:3], v[34:35], 0, s[0:1]
	v_lshl_add_u64 v[2:3], v[2:3], 0, v[176:177]
	s_add_i32 s0, s3, 0x130
	v_lshl_add_u64 v[2:3], v[2:3], 0, v[36:37]
	s_lshr_b32 s96, s0, 4
	global_store_dwordx2 v[2:3], v[0:1], off offset:512
	v_pk_mul_f32 v[0:1], v[24:25], v[32:33] op_sel_hi:[1,0]
	v_pk_mul_f32 v[2:3], v[26:27], v[32:33] op_sel_hi:[1,0]
	s_lshl_b64 s[0:1], s[96:97], 10
	v_cvt_pk_bf16_f32 v0, v0, v1
	v_cvt_pk_bf16_f32 v1, v2, v3
	v_lshl_add_u64 v[2:3], v[34:35], 0, s[0:1]
	v_lshl_add_u64 v[2:3], v[2:3], 0, v[176:177]
	s_addk_i32 s3, 0x138
	v_lshl_add_u64 v[2:3], v[2:3], 0, v[36:37]
	s_lshr_b32 s96, s3, 4
	global_store_dwordx2 v[2:3], v[0:1], off
	v_pk_mul_f32 v[0:1], v[28:29], v[32:33] op_sel_hi:[1,0]
	v_pk_mul_f32 v[2:3], v[30:31], v[32:33] op_sel_hi:[1,0]
	s_lshl_b64 s[0:1], s[96:97], 10
	v_cvt_pk_bf16_f32 v0, v0, v1
	v_cvt_pk_bf16_f32 v1, v2, v3
	v_lshl_add_u64 v[2:3], v[34:35], 0, s[0:1]
	v_lshl_add_u64 v[2:3], v[2:3], 0, v[176:177]
	v_lshl_add_u64 v[2:3], v[2:3], 0, v[36:37]
	global_store_dwordx2 v[2:3], v[0:1], off offset:512

.LBB0_923:
	s_ashr_i32 s2, s4, 31
	s_lshr_b32 s2, s2, 26
	s_add_i32 s2, s4, s2
	s_ashr_i32 s3, s2, 6
	s_lshl_b32 s3, s3, 3
	s_sub_i32 s8, s25, s3
	s_min_i32 s8, s8, 8
	s_abs_i32 s9, s8
	v_cvt_f32_u32_e32 v0, s9
	s_sub_i32 s12, 0, s9
	s_andn2_b32 s2, s2, 63
	s_sub_i32 s10, s4, s2
	v_rcp_iflag_f32_e32 v0, v0
	s_abs_i32 s2, s10
	s_xor_b32 s11, s10, s8
	s_ashr_i32 s11, s11, 31
	v_mul_f32_e32 v0, 0x4f7ffffe, v0
	v_cvt_u32_f32_e32 v0, v0
	v_mov_b32_e32 v181, v179
	v_readfirstlane_b32 s13, v0
	s_mul_i32 s12, s12, s13
	s_mul_hi_u32 s12, s13, s12
	s_add_i32 s13, s13, s12
	s_mul_hi_u32 s12, s2, s13
	s_mul_i32 s13, s12, s9
	s_sub_i32 s2, s2, s13
	s_add_i32 s14, s12, 1
	s_sub_i32 s13, s2, s9
	s_cmp_ge_u32 s2, s9
	s_cselect_b32 s12, s14, s12
	s_cselect_b32 s2, s13, s2
	s_add_i32 s13, s12, 1
	s_cmp_ge_u32 s2, s9
	s_cselect_b32 s2, s13, s12
	s_xor_b32 s2, s2, s11
	s_sub_i32 s2, s2, s11
	s_mul_i32 s8, s8, s2
	s_add_i32 s3, s3, s7
	s_sub_i32 s8, s10, s8
	v_ashrrev_i32_e32 v237, 6, v181
	s_add_i32 s8, s3, s8
	v_lshlrev_b32_e32 v0, 1, v237
	v_lshl_add_u32 v0, s8, 3, v0
	v_ashrrev_i32_e32 v1, 31, v0
	v_bfe_u32 v183, v181, 5, 1
	v_lshlrev_b64 v[0:1], 16, v[0:1]
	v_and_b32_e32 v238, 31, v181
	v_lshl_add_u64 v[0:1], s[64:65], 0, v[0:1]
	v_lshlrev_b32_e32 v176, 9, v183
	s_ashr_i32 s3, s2, 31
	v_lshl_add_u64 v[0:1], v[0:1], 0, v[176:177]
	v_lshlrev_b32_e32 v176, 4, v238
	v_ashrrev_i32_e32 v40, 2, v181
	s_lshl_b64 s[10:11], s[2:3], 18
	v_lshl_add_u64 v[184:185], v[0:1], 0, v[176:177]
	s_add_u32 s10, s5, s10
	v_lshlrev_b32_e32 v0, 5, v40
	s_addc_u32 s11, s6, s11
	v_ashrrev_i32_e32 v1, 31, v0
	v_lshlrev_b32_e32 v2, 4, v181
	v_lshl_add_u64 v[0:1], v[0:1], 1, s[10:11]
	v_and_b32_e32 v176, 48, v2
	v_lshl_add_u64 v[186:187], v[0:1], 0, v[176:177]
	s_movk_i32 s3, 0x2000
	v_add_co_u32_e32 v36, vcc, s3, v186
	v_mul_u32_u24_e32 v38, 40, v238
	s_nop 0
	v_addc_co_u32_e32 v37, vcc, 0, v187, vcc
	v_lshlrev_b32_e32 v39, 4, v183
	v_lshl_add_u32 v240, v38, 1, v39
	v_add_co_u32_e32 v38, vcc, s41, v184
	s_movk_i32 s9, 0x50
	s_nop 0
	v_addc_co_u32_e32 v39, vcc, 0, v185, vcc
	v_and_b32_e32 v239, 63, v181
	s_cmp_eq_u32 s100, 1
	s_cbranch_scc1 .Lhx_out_half
	v_bfe_u32 v247, v181, 4, 2
	v_lshlrev_b32_e32 v247, 1, v247
	v_mov_b32_e32 v176, 0x78
	v_lshrrev_b32_e32 v247, v247, v176
	v_and_b32_e32 v247, 3, v247
	v_and_b32_e32 v246, 3, v181
	v_xor_b32_e32 v247, v247, v246
	v_lshlrev_b32_e32 v247, 4, v247
	v_and_b32_e32 v188, 0xffffffcf, v186
	v_or_b32_e32 v188, v188, v247
	v_mov_b32_e32 v189, v187
	v_lshrrev_b32_e32 v176, 6, v181
	v_lshlrev_b32_e32 v247, 11, v176
	v_lshlrev_b32_e32 v176, 10, v176
	v_lshl_add_u64 v[188:189], v[188:189], 0, v[176:177]
	v_readfirstlane_b32 vcc_lo, v247
	v_bfe_u32 v247, v181, 4, 1
	v_lshlrev_b32_e32 v176, 9, v183
	v_lshl_add_u32 v176, v247, 8, v176
	v_lshl_add_u64 v[184:185], v[184:185], 0, v[176:177]
	v_mov_b32_e32 v176, s41
	v_lshl_add_u64 v[186:187], v[184:185], 0, v[176:177]
	v_mov_b32_e32 v176, 0x78
	v_bfe_u32 v247, v181, 2, 1
	v_lshlrev_b32_e32 v247, 2, v247
	v_lshrrev_b32_e32 v247, v247, v176
	v_and_b32_e32 v247, 3, v247
	v_bfe_u32 v246, v181, 4, 2
	v_xor_b32_e32 v247, v247, v246
	v_lshlrev_b32_e32 v247, 4, v247
	v_bfe_u32 v246, v181, 2, 2
	v_lshlrev_b32_e32 v246, 3, v246
	v_and_b32_e32 v162, 3, v181
	v_add_u32_e32 v246, v246, v162
	v_lshl_add_u32 v246, v246, 6, v247
	v_bfe_u32 v247, v181, 2, 1
	v_lshlrev_b32_e32 v247, 2, v247
	v_add_u32_e32 v247, 2, v247
	v_lshrrev_b32_e32 v247, v247, v176
	v_and_b32_e32 v247, 3, v247
	v_bfe_u32 v162, v181, 4, 2
	v_xor_b32_e32 v247, v247, v162
	v_lshlrev_b32_e32 v247, 4, v247
	v_and_b32_e32 v162, 0xffffffcf, v246
	v_add_u32_e32 v162, 0x100, v162
	v_or_b32_e32 v162, v162, v247
	s_mov_b32 s96, 0
	s_mov_b32 m0, vcc_lo
	v_lshl_add_u64 v[160:161], v[188:189], 0, s[96:97]
	global_load_lds_dwordx4 v[160:161], off
	global_load_lds_dwordx4 v[160:161], off offset:1024
	s_mov_b32 s96, 0
	v_lshl_add_u64 v[248:249], v[184:185], 0, s[96:97]
	v_lshl_add_u64 v[250:251], v[186:187], 0, s[96:97]
	global_load_dwordx4 v[128:131], v[248:249], off
	global_load_dwordx4 v[132:135], v[248:249], off offset:256
	global_load_dwordx4 v[136:139], v[250:251], off
	global_load_dwordx4 v[140:143], v[250:251], off offset:256
	s_movk_i32 s96, 0x2000
	s_add_i32 m0, vcc_lo, 8192
	v_lshl_add_u64 v[160:161], v[188:189], 0, s[96:97]
	global_load_lds_dwordx4 v[160:161], off
	global_load_lds_dwordx4 v[160:161], off offset:1024
	s_movk_i32 s96, 0x800
	v_lshl_add_u64 v[248:249], v[184:185], 0, s[96:97]
	v_lshl_add_u64 v[250:251], v[186:187], 0, s[96:97]
	global_load_dwordx4 v[144:147], v[248:249], off
	global_load_dwordx4 v[148:151], v[248:249], off offset:256
	global_load_dwordx4 v[152:155], v[250:251], off
	global_load_dwordx4 v[156:159], v[250:251], off offset:256
	v_mov_b32_e32 v0, 0
	v_mov_b32_e32 v1, 0
	v_mov_b32_e32 v2, 0
	v_mov_b32_e32 v3, 0
	v_mov_b32_e32 v4, 0
	v_mov_b32_e32 v5, 0
	v_mov_b32_e32 v6, 0
	v_mov_b32_e32 v7, 0
	v_mov_b32_e32 v8, 0
	v_mov_b32_e32 v9, 0
	v_mov_b32_e32 v10, 0
	v_mov_b32_e32 v11, 0
	v_mov_b32_e32 v12, 0
	v_mov_b32_e32 v13, 0
	v_mov_b32_e32 v14, 0
	v_mov_b32_e32 v15, 0
	v_mov_b32_e32 v16, 0
	v_mov_b32_e32 v17, 0
	v_mov_b32_e32 v18, 0
	v_mov_b32_e32 v19, 0
	v_mov_b32_e32 v20, 0
	v_mov_b32_e32 v21, 0
	v_mov_b32_e32 v22, 0
	v_mov_b32_e32 v23, 0
	v_mov_b32_e32 v24, 0
	v_mov_b32_e32 v25, 0
	v_mov_b32_e32 v26, 0
	v_mov_b32_e32 v27, 0
	v_mov_b32_e32 v28, 0
	v_mov_b32_e32 v29, 0
	v_mov_b32_e32 v30, 0
	v_mov_b32_e32 v31, 0
	v_mov_b32_e32 v32, 0
	v_mov_b32_e32 v33, 0
	v_mov_b32_e32 v34, 0
	v_mov_b32_e32 v35, 0
	v_mov_b32_e32 v36, 0
	v_mov_b32_e32 v37, 0
	v_mov_b32_e32 v38, 0
	v_mov_b32_e32 v39, 0
	v_mov_b32_e32 v40, 0
	v_mov_b32_e32 v41, 0
	v_mov_b32_e32 v42, 0
	v_mov_b32_e32 v43, 0
	v_mov_b32_e32 v44, 0
	v_mov_b32_e32 v45, 0
	v_mov_b32_e32 v46, 0
	v_mov_b32_e32 v47, 0
	v_mov_b32_e32 v48, 0
	v_mov_b32_e32 v49, 0
	v_mov_b32_e32 v50, 0
	v_mov_b32_e32 v51, 0
	v_mov_b32_e32 v52, 0
	v_mov_b32_e32 v53, 0
	v_mov_b32_e32 v54, 0
	v_mov_b32_e32 v55, 0
	v_mov_b32_e32 v56, 0
	v_mov_b32_e32 v57, 0
	v_mov_b32_e32 v58, 0
	v_mov_b32_e32 v59, 0
	v_mov_b32_e32 v60, 0
	v_mov_b32_e32 v61, 0
	v_mov_b32_e32 v62, 0
	v_mov_b32_e32 v63, 0
	v_mov_b32_e32 v64, 0
	v_mov_b32_e32 v65, 0
	v_mov_b32_e32 v66, 0
	v_mov_b32_e32 v67, 0
	v_mov_b32_e32 v68, 0
	v_mov_b32_e32 v69, 0
	v_mov_b32_e32 v70, 0
	v_mov_b32_e32 v71, 0
	v_mov_b32_e32 v72, 0
	v_mov_b32_e32 v73, 0
	v_mov_b32_e32 v74, 0
	v_mov_b32_e32 v75, 0
	v_mov_b32_e32 v76, 0
	v_mov_b32_e32 v77, 0
	v_mov_b32_e32 v78, 0
	v_mov_b32_e32 v79, 0
	v_mov_b32_e32 v80, 0
	v_mov_b32_e32 v81, 0
	v_mov_b32_e32 v82, 0
	v_mov_b32_e32 v83, 0
	v_mov_b32_e32 v84, 0
	v_mov_b32_e32 v85, 0
	v_mov_b32_e32 v86, 0
	v_mov_b32_e32 v87, 0
	v_mov_b32_e32 v88, 0
	v_mov_b32_e32 v89, 0
	v_mov_b32_e32 v90, 0
	v_mov_b32_e32 v91, 0
	v_mov_b32_e32 v92, 0
	v_mov_b32_e32 v93, 0
	v_mov_b32_e32 v94, 0
	v_mov_b32_e32 v95, 0
	v_mov_b32_e32 v96, 0
	v_mov_b32_e32 v97, 0
	v_mov_b32_e32 v98, 0
	v_mov_b32_e32 v99, 0
	v_mov_b32_e32 v100, 0
	v_mov_b32_e32 v101, 0
	v_mov_b32_e32 v102, 0
	v_mov_b32_e32 v103, 0
	v_mov_b32_e32 v104, 0
	v_mov_b32_e32 v105, 0
	v_mov_b32_e32 v106, 0
	v_mov_b32_e32 v107, 0
	v_mov_b32_e32 v108, 0
	v_mov_b32_e32 v109, 0
	v_mov_b32_e32 v110, 0
	v_mov_b32_e32 v111, 0
	v_mov_b32_e32 v112, 0
	v_mov_b32_e32 v113, 0
	v_mov_b32_e32 v114, 0
	v_mov_b32_e32 v115, 0
	v_mov_b32_e32 v116, 0
	v_mov_b32_e32 v117, 0
	v_mov_b32_e32 v118, 0
	v_mov_b32_e32 v119, 0
	v_mov_b32_e32 v120, 0
	v_mov_b32_e32 v121, 0
	v_mov_b32_e32 v122, 0
	v_mov_b32_e32 v123, 0
	v_mov_b32_e32 v124, 0
	v_mov_b32_e32 v125, 0
	v_mov_b32_e32 v126, 0
	v_mov_b32_e32 v127, 0
	s_mov_b32 s3, 0
	s_waitcnt vmcnt(4)
	s_barrier
	s_nop 0
.Lg16_out_k:
	s_add_i32 s9, s3, 2
	s_lshl_b32 s96, s9, 13
	s_add_i32 m0, vcc_lo, 16384
	v_lshl_add_u64 v[160:161], v[188:189], 0, s[96:97]
	global_load_lds_dwordx4 v[160:161], off
	global_load_lds_dwordx4 v[160:161], off offset:1024
	ds_read_b128 v[196:199], v246 offset:0
	ds_read_b128 v[200:203], v162 offset:0
	ds_read_b128 v[204:207], v246 offset:2048
	ds_read_b128 v[242:245], v162 offset:2048
	s_add_i32 s9, s3, 2
	s_lshl_b32 s96, s9, 11
	v_lshl_add_u64 v[248:249], v[184:185], 0, s[96:97]
	v_lshl_add_u64 v[250:251], v[186:187], 0, s[96:97]
	s_waitcnt vmcnt(8) lgkmcnt(3)
	v_mfma_f32_16x16x32_bf16 v[112:115], v[196:199], v[128:131], v[112:115]
	v_mfma_f32_16x16x32_bf16 v[120:123], v[196:199], v[132:135], v[120:123]
	v_mfma_f32_16x16x32_bf16 v[48:51], v[196:199], v[136:139], v[48:51]
	v_mfma_f32_16x16x32_bf16 v[56:59], v[196:199], v[140:143], v[56:59]
	ds_read_b128 v[196:199], v246 offset:4096
	s_waitcnt lgkmcnt(3)
	v_mfma_f32_16x16x32_bf16 v[116:119], v[200:203], v[128:131], v[116:119]
	v_mfma_f32_16x16x32_bf16 v[124:127], v[200:203], v[132:135], v[124:127]
	v_mfma_f32_16x16x32_bf16 v[52:55], v[200:203], v[136:139], v[52:55]
	v_mfma_f32_16x16x32_bf16 v[60:63], v[200:203], v[140:143], v[60:63]
	ds_read_b128 v[200:203], v162 offset:4096
	s_waitcnt lgkmcnt(3)
	v_mfma_f32_16x16x32_bf16 v[96:99], v[204:207], v[128:131], v[96:99]
	v_mfma_f32_16x16x32_bf16 v[104:107], v[204:207], v[132:135], v[104:107]
	v_mfma_f32_16x16x32_bf16 v[32:35], v[204:207], v[136:139], v[32:35]
	v_mfma_f32_16x16x32_bf16 v[40:43], v[204:207], v[140:143], v[40:43]
	ds_read_b128 v[204:207], v246 offset:6144
	s_waitcnt lgkmcnt(3)
	v_mfma_f32_16x16x32_bf16 v[100:103], v[242:245], v[128:131], v[100:103]
	v_mfma_f32_16x16x32_bf16 v[108:111], v[242:245], v[132:135], v[108:111]
	v_mfma_f32_16x16x32_bf16 v[36:39], v[242:245], v[136:139], v[36:39]
	v_mfma_f32_16x16x32_bf16 v[44:47], v[242:245], v[140:143], v[44:47]
	ds_read_b128 v[242:245], v162 offset:6144
	s_waitcnt lgkmcnt(3)
	v_mfma_f32_16x16x32_bf16 v[80:83], v[196:199], v[128:131], v[80:83]
	v_mfma_f32_16x16x32_bf16 v[88:91], v[196:199], v[132:135], v[88:91]
	v_mfma_f32_16x16x32_bf16 v[16:19], v[196:199], v[136:139], v[16:19]
	v_mfma_f32_16x16x32_bf16 v[24:27], v[196:199], v[140:143], v[24:27]
	s_waitcnt lgkmcnt(2)
	v_mfma_f32_16x16x32_bf16 v[84:87], v[200:203], v[128:131], v[84:87]
	v_mfma_f32_16x16x32_bf16 v[92:95], v[200:203], v[132:135], v[92:95]
	v_mfma_f32_16x16x32_bf16 v[20:23], v[200:203], v[136:139], v[20:23]
	v_mfma_f32_16x16x32_bf16 v[28:31], v[200:203], v[140:143], v[28:31]
	s_waitcnt lgkmcnt(1)
	v_mfma_f32_16x16x32_bf16 v[64:67], v[204:207], v[128:131], v[64:67]
	v_mfma_f32_16x16x32_bf16 v[72:75], v[204:207], v[132:135], v[72:75]
	v_mfma_f32_16x16x32_bf16 v[0:3], v[204:207], v[136:139], v[0:3]
	v_mfma_f32_16x16x32_bf16 v[8:11], v[204:207], v[140:143], v[8:11]
	s_waitcnt lgkmcnt(0)
	v_mfma_f32_16x16x32_bf16 v[68:71], v[242:245], v[128:131], v[68:71]
	v_mfma_f32_16x16x32_bf16 v[76:79], v[242:245], v[132:135], v[76:79]
	v_mfma_f32_16x16x32_bf16 v[4:7], v[242:245], v[136:139], v[4:7]
	v_mfma_f32_16x16x32_bf16 v[12:15], v[242:245], v[140:143], v[12:15]
	global_load_dwordx4 v[128:131], v[248:249], off
	global_load_dwordx4 v[132:135], v[248:249], off offset:256
	global_load_dwordx4 v[136:139], v[250:251], off
	global_load_dwordx4 v[140:143], v[250:251], off offset:256
	s_waitcnt vmcnt(10)
	s_barrier
	s_add_i32 s9, s3, 3
	s_lshl_b32 s96, s9, 13
	s_mov_b32 m0, vcc_lo
	v_lshl_add_u64 v[160:161], v[188:189], 0, s[96:97]
	global_load_lds_dwordx4 v[160:161], off
	global_load_lds_dwordx4 v[160:161], off offset:1024
	ds_read_b128 v[196:199], v246 offset:8192
	ds_read_b128 v[200:203], v162 offset:8192
	ds_read_b128 v[204:207], v246 offset:10240
	ds_read_b128 v[242:245], v162 offset:10240
	s_add_i32 s9, s3, 3
	s_lshl_b32 s96, s9, 11
	v_lshl_add_u64 v[248:249], v[184:185], 0, s[96:97]
	v_lshl_add_u64 v[250:251], v[186:187], 0, s[96:97]
	s_waitcnt vmcnt(8) lgkmcnt(3)
	v_mfma_f32_16x16x32_bf16 v[112:115], v[196:199], v[144:147], v[112:115]
	v_mfma_f32_16x16x32_bf16 v[120:123], v[196:199], v[148:151], v[120:123]
	v_mfma_f32_16x16x32_bf16 v[48:51], v[196:199], v[152:155], v[48:51]
	v_mfma_f32_16x16x32_bf16 v[56:59], v[196:199], v[156:159], v[56:59]
	ds_read_b128 v[196:199], v246 offset:12288
	s_waitcnt lgkmcnt(3)
	v_mfma_f32_16x16x32_bf16 v[116:119], v[200:203], v[144:147], v[116:119]
	v_mfma_f32_16x16x32_bf16 v[124:127], v[200:203], v[148:151], v[124:127]
	v_mfma_f32_16x16x32_bf16 v[52:55], v[200:203], v[152:155], v[52:55]
	v_mfma_f32_16x16x32_bf16 v[60:63], v[200:203], v[156:159], v[60:63]
	ds_read_b128 v[200:203], v162 offset:12288
	s_waitcnt lgkmcnt(3)
	v_mfma_f32_16x16x32_bf16 v[96:99], v[204:207], v[144:147], v[96:99]
	v_mfma_f32_16x16x32_bf16 v[104:107], v[204:207], v[148:151], v[104:107]
	v_mfma_f32_16x16x32_bf16 v[32:35], v[204:207], v[152:155], v[32:35]
	v_mfma_f32_16x16x32_bf16 v[40:43], v[204:207], v[156:159], v[40:43]
	ds_read_b128 v[204:207], v246 offset:14336
	s_waitcnt lgkmcnt(3)
	v_mfma_f32_16x16x32_bf16 v[100:103], v[242:245], v[144:147], v[100:103]
	v_mfma_f32_16x16x32_bf16 v[108:111], v[242:245], v[148:151], v[108:111]
	v_mfma_f32_16x16x32_bf16 v[36:39], v[242:245], v[152:155], v[36:39]
	v_mfma_f32_16x16x32_bf16 v[44:47], v[242:245], v[156:159], v[44:47]
	ds_read_b128 v[242:245], v162 offset:14336
	s_waitcnt lgkmcnt(3)
	v_mfma_f32_16x16x32_bf16 v[80:83], v[196:199], v[144:147], v[80:83]
	v_mfma_f32_16x16x32_bf16 v[88:91], v[196:199], v[148:151], v[88:91]
	v_mfma_f32_16x16x32_bf16 v[16:19], v[196:199], v[152:155], v[16:19]
	v_mfma_f32_16x16x32_bf16 v[24:27], v[196:199], v[156:159], v[24:27]
	s_waitcnt lgkmcnt(2)
	v_mfma_f32_16x16x32_bf16 v[84:87], v[200:203], v[144:147], v[84:87]
	v_mfma_f32_16x16x32_bf16 v[92:95], v[200:203], v[148:151], v[92:95]
	v_mfma_f32_16x16x32_bf16 v[20:23], v[200:203], v[152:155], v[20:23]
	v_mfma_f32_16x16x32_bf16 v[28:31], v[200:203], v[156:159], v[28:31]
	s_waitcnt lgkmcnt(1)
	v_mfma_f32_16x16x32_bf16 v[64:67], v[204:207], v[144:147], v[64:67]
	v_mfma_f32_16x16x32_bf16 v[72:75], v[204:207], v[148:151], v[72:75]
	v_mfma_f32_16x16x32_bf16 v[0:3], v[204:207], v[152:155], v[0:3]
	v_mfma_f32_16x16x32_bf16 v[8:11], v[204:207], v[156:159], v[8:11]
	s_waitcnt lgkmcnt(0)
	v_mfma_f32_16x16x32_bf16 v[68:71], v[242:245], v[144:147], v[68:71]
	v_mfma_f32_16x16x32_bf16 v[76:79], v[242:245], v[148:151], v[76:79]
	v_mfma_f32_16x16x32_bf16 v[4:7], v[242:245], v[152:155], v[4:7]
	v_mfma_f32_16x16x32_bf16 v[12:15], v[242:245], v[156:159], v[12:15]
	global_load_dwordx4 v[144:147], v[248:249], off
	global_load_dwordx4 v[148:151], v[248:249], off offset:256
	global_load_dwordx4 v[152:155], v[250:251], off
	global_load_dwordx4 v[156:159], v[250:251], off offset:256
	s_waitcnt vmcnt(10)
	s_barrier
	s_add_i32 s9, s3, 4
	s_lshl_b32 s96, s9, 13
	s_add_i32 m0, vcc_lo, 8192
	v_lshl_add_u64 v[160:161], v[188:189], 0, s[96:97]
	global_load_lds_dwordx4 v[160:161], off
	global_load_lds_dwordx4 v[160:161], off offset:1024
	ds_read_b128 v[196:199], v246 offset:16384
	ds_read_b128 v[200:203], v162 offset:16384
	ds_read_b128 v[204:207], v246 offset:18432
	ds_read_b128 v[242:245], v162 offset:18432
	s_add_i32 s9, s3, 4
	s_lshl_b32 s96, s9, 11
	v_lshl_add_u64 v[248:249], v[184:185], 0, s[96:97]
	v_lshl_add_u64 v[250:251], v[186:187], 0, s[96:97]
	s_waitcnt vmcnt(8) lgkmcnt(3)
	v_mfma_f32_16x16x32_bf16 v[112:115], v[196:199], v[128:131], v[112:115]
	v_mfma_f32_16x16x32_bf16 v[120:123], v[196:199], v[132:135], v[120:123]
	v_mfma_f32_16x16x32_bf16 v[48:51], v[196:199], v[136:139], v[48:51]
	v_mfma_f32_16x16x32_bf16 v[56:59], v[196:199], v[140:143], v[56:59]
	ds_read_b128 v[196:199], v246 offset:20480
	s_waitcnt lgkmcnt(3)
	v_mfma_f32_16x16x32_bf16 v[116:119], v[200:203], v[128:131], v[116:119]
	v_mfma_f32_16x16x32_bf16 v[124:127], v[200:203], v[132:135], v[124:127]
	v_mfma_f32_16x16x32_bf16 v[52:55], v[200:203], v[136:139], v[52:55]
	v_mfma_f32_16x16x32_bf16 v[60:63], v[200:203], v[140:143], v[60:63]
	ds_read_b128 v[200:203], v162 offset:20480
	s_waitcnt lgkmcnt(3)
	v_mfma_f32_16x16x32_bf16 v[96:99], v[204:207], v[128:131], v[96:99]
	v_mfma_f32_16x16x32_bf16 v[104:107], v[204:207], v[132:135], v[104:107]
	v_mfma_f32_16x16x32_bf16 v[32:35], v[204:207], v[136:139], v[32:35]
	v_mfma_f32_16x16x32_bf16 v[40:43], v[204:207], v[140:143], v[40:43]
	ds_read_b128 v[204:207], v246 offset:22528
	s_waitcnt lgkmcnt(3)
	v_mfma_f32_16x16x32_bf16 v[100:103], v[242:245], v[128:131], v[100:103]
	v_mfma_f32_16x16x32_bf16 v[108:111], v[242:245], v[132:135], v[108:111]
	v_mfma_f32_16x16x32_bf16 v[36:39], v[242:245], v[136:139], v[36:39]
	v_mfma_f32_16x16x32_bf16 v[44:47], v[242:245], v[140:143], v[44:47]
	ds_read_b128 v[242:245], v162 offset:22528
	s_waitcnt lgkmcnt(3)
	v_mfma_f32_16x16x32_bf16 v[80:83], v[196:199], v[128:131], v[80:83]
	v_mfma_f32_16x16x32_bf16 v[88:91], v[196:199], v[132:135], v[88:91]
	v_mfma_f32_16x16x32_bf16 v[16:19], v[196:199], v[136:139], v[16:19]
	v_mfma_f32_16x16x32_bf16 v[24:27], v[196:199], v[140:143], v[24:27]
	s_waitcnt lgkmcnt(2)
	v_mfma_f32_16x16x32_bf16 v[84:87], v[200:203], v[128:131], v[84:87]
	v_mfma_f32_16x16x32_bf16 v[92:95], v[200:203], v[132:135], v[92:95]
	v_mfma_f32_16x16x32_bf16 v[20:23], v[200:203], v[136:139], v[20:23]
	v_mfma_f32_16x16x32_bf16 v[28:31], v[200:203], v[140:143], v[28:31]
	s_waitcnt lgkmcnt(1)
	v_mfma_f32_16x16x32_bf16 v[64:67], v[204:207], v[128:131], v[64:67]
	v_mfma_f32_16x16x32_bf16 v[72:75], v[204:207], v[132:135], v[72:75]
	v_mfma_f32_16x16x32_bf16 v[0:3], v[204:207], v[136:139], v[0:3]
	v_mfma_f32_16x16x32_bf16 v[8:11], v[204:207], v[140:143], v[8:11]
	s_waitcnt lgkmcnt(0)
	v_mfma_f32_16x16x32_bf16 v[68:71], v[242:245], v[128:131], v[68:71]
	v_mfma_f32_16x16x32_bf16 v[76:79], v[242:245], v[132:135], v[76:79]
	v_mfma_f32_16x16x32_bf16 v[4:7], v[242:245], v[136:139], v[4:7]
	v_mfma_f32_16x16x32_bf16 v[12:15], v[242:245], v[140:143], v[12:15]
	global_load_dwordx4 v[128:131], v[248:249], off
	global_load_dwordx4 v[132:135], v[248:249], off offset:256
	global_load_dwordx4 v[136:139], v[250:251], off
	global_load_dwordx4 v[140:143], v[250:251], off offset:256
	s_waitcnt vmcnt(10)
	s_barrier
	s_add_i32 s9, s3, 5
	s_lshl_b32 s96, s9, 13
	s_add_i32 m0, vcc_lo, 16384
	v_lshl_add_u64 v[160:161], v[188:189], 0, s[96:97]
	global_load_lds_dwordx4 v[160:161], off
	global_load_lds_dwordx4 v[160:161], off offset:1024
	ds_read_b128 v[196:199], v246 offset:0
	ds_read_b128 v[200:203], v162 offset:0
	ds_read_b128 v[204:207], v246 offset:2048
	ds_read_b128 v[242:245], v162 offset:2048
	s_add_i32 s9, s3, 5
	s_lshl_b32 s96, s9, 11
	v_lshl_add_u64 v[248:249], v[184:185], 0, s[96:97]
	v_lshl_add_u64 v[250:251], v[186:187], 0, s[96:97]
	s_waitcnt vmcnt(8) lgkmcnt(3)
	v_mfma_f32_16x16x32_bf16 v[112:115], v[196:199], v[144:147], v[112:115]
	v_mfma_f32_16x16x32_bf16 v[120:123], v[196:199], v[148:151], v[120:123]
	v_mfma_f32_16x16x32_bf16 v[48:51], v[196:199], v[152:155], v[48:51]
	v_mfma_f32_16x16x32_bf16 v[56:59], v[196:199], v[156:159], v[56:59]
	ds_read_b128 v[196:199], v246 offset:4096
	s_waitcnt lgkmcnt(3)
	v_mfma_f32_16x16x32_bf16 v[116:119], v[200:203], v[144:147], v[116:119]
	v_mfma_f32_16x16x32_bf16 v[124:127], v[200:203], v[148:151], v[124:127]
	v_mfma_f32_16x16x32_bf16 v[52:55], v[200:203], v[152:155], v[52:55]
	v_mfma_f32_16x16x32_bf16 v[60:63], v[200:203], v[156:159], v[60:63]
	ds_read_b128 v[200:203], v162 offset:4096
	s_waitcnt lgkmcnt(3)
	v_mfma_f32_16x16x32_bf16 v[96:99], v[204:207], v[144:147], v[96:99]
	v_mfma_f32_16x16x32_bf16 v[104:107], v[204:207], v[148:151], v[104:107]
	v_mfma_f32_16x16x32_bf16 v[32:35], v[204:207], v[152:155], v[32:35]
	v_mfma_f32_16x16x32_bf16 v[40:43], v[204:207], v[156:159], v[40:43]
	ds_read_b128 v[204:207], v246 offset:6144
	s_waitcnt lgkmcnt(3)
	v_mfma_f32_16x16x32_bf16 v[100:103], v[242:245], v[144:147], v[100:103]
	v_mfma_f32_16x16x32_bf16 v[108:111], v[242:245], v[148:151], v[108:111]
	v_mfma_f32_16x16x32_bf16 v[36:39], v[242:245], v[152:155], v[36:39]
	v_mfma_f32_16x16x32_bf16 v[44:47], v[242:245], v[156:159], v[44:47]
	ds_read_b128 v[242:245], v162 offset:6144
	s_waitcnt lgkmcnt(3)
	v_mfma_f32_16x16x32_bf16 v[80:83], v[196:199], v[144:147], v[80:83]
	v_mfma_f32_16x16x32_bf16 v[88:91], v[196:199], v[148:151], v[88:91]
	v_mfma_f32_16x16x32_bf16 v[16:19], v[196:199], v[152:155], v[16:19]
	v_mfma_f32_16x16x32_bf16 v[24:27], v[196:199], v[156:159], v[24:27]
	s_waitcnt lgkmcnt(2)
	v_mfma_f32_16x16x32_bf16 v[84:87], v[200:203], v[144:147], v[84:87]
	v_mfma_f32_16x16x32_bf16 v[92:95], v[200:203], v[148:151], v[92:95]
	v_mfma_f32_16x16x32_bf16 v[20:23], v[200:203], v[152:155], v[20:23]
	v_mfma_f32_16x16x32_bf16 v[28:31], v[200:203], v[156:159], v[28:31]
	s_waitcnt lgkmcnt(1)
	v_mfma_f32_16x16x32_bf16 v[64:67], v[204:207], v[144:147], v[64:67]
	v_mfma_f32_16x16x32_bf16 v[72:75], v[204:207], v[148:151], v[72:75]
	v_mfma_f32_16x16x32_bf16 v[0:3], v[204:207], v[152:155], v[0:3]
	v_mfma_f32_16x16x32_bf16 v[8:11], v[204:207], v[156:159], v[8:11]
	s_waitcnt lgkmcnt(0)
	v_mfma_f32_16x16x32_bf16 v[68:71], v[242:245], v[144:147], v[68:71]
	v_mfma_f32_16x16x32_bf16 v[76:79], v[242:245], v[148:151], v[76:79]
	v_mfma_f32_16x16x32_bf16 v[4:7], v[242:245], v[152:155], v[4:7]
	v_mfma_f32_16x16x32_bf16 v[12:15], v[242:245], v[156:159], v[12:15]
	global_load_dwordx4 v[144:147], v[248:249], off
	global_load_dwordx4 v[148:151], v[248:249], off offset:256
	global_load_dwordx4 v[152:155], v[250:251], off
	global_load_dwordx4 v[156:159], v[250:251], off offset:256
	s_waitcnt vmcnt(10)
	s_barrier
	s_add_i32 s9, s3, 6
	s_lshl_b32 s96, s9, 13
	s_mov_b32 m0, vcc_lo
	v_lshl_add_u64 v[160:161], v[188:189], 0, s[96:97]
	global_load_lds_dwordx4 v[160:161], off
	global_load_lds_dwordx4 v[160:161], off offset:1024
	ds_read_b128 v[196:199], v246 offset:8192
	ds_read_b128 v[200:203], v162 offset:8192
	ds_read_b128 v[204:207], v246 offset:10240
	ds_read_b128 v[242:245], v162 offset:10240
	s_add_i32 s9, s3, 6
	s_lshl_b32 s96, s9, 11
	v_lshl_add_u64 v[248:249], v[184:185], 0, s[96:97]
	v_lshl_add_u64 v[250:251], v[186:187], 0, s[96:97]
	s_waitcnt vmcnt(8) lgkmcnt(3)
	v_mfma_f32_16x16x32_bf16 v[112:115], v[196:199], v[128:131], v[112:115]
	v_mfma_f32_16x16x32_bf16 v[120:123], v[196:199], v[132:135], v[120:123]
	v_mfma_f32_16x16x32_bf16 v[48:51], v[196:199], v[136:139], v[48:51]
	v_mfma_f32_16x16x32_bf16 v[56:59], v[196:199], v[140:143], v[56:59]
	ds_read_b128 v[196:199], v246 offset:12288
	s_waitcnt lgkmcnt(3)
	v_mfma_f32_16x16x32_bf16 v[116:119], v[200:203], v[128:131], v[116:119]
	v_mfma_f32_16x16x32_bf16 v[124:127], v[200:203], v[132:135], v[124:127]
	v_mfma_f32_16x16x32_bf16 v[52:55], v[200:203], v[136:139], v[52:55]
	v_mfma_f32_16x16x32_bf16 v[60:63], v[200:203], v[140:143], v[60:63]
	ds_read_b128 v[200:203], v162 offset:12288
	s_waitcnt lgkmcnt(3)
	v_mfma_f32_16x16x32_bf16 v[96:99], v[204:207], v[128:131], v[96:99]
	v_mfma_f32_16x16x32_bf16 v[104:107], v[204:207], v[132:135], v[104:107]
	v_mfma_f32_16x16x32_bf16 v[32:35], v[204:207], v[136:139], v[32:35]
	v_mfma_f32_16x16x32_bf16 v[40:43], v[204:207], v[140:143], v[40:43]
	ds_read_b128 v[204:207], v246 offset:14336
	s_waitcnt lgkmcnt(3)
	v_mfma_f32_16x16x32_bf16 v[100:103], v[242:245], v[128:131], v[100:103]
	v_mfma_f32_16x16x32_bf16 v[108:111], v[242:245], v[132:135], v[108:111]
	v_mfma_f32_16x16x32_bf16 v[36:39], v[242:245], v[136:139], v[36:39]
	v_mfma_f32_16x16x32_bf16 v[44:47], v[242:245], v[140:143], v[44:47]
	ds_read_b128 v[242:245], v162 offset:14336
	s_waitcnt lgkmcnt(3)
	v_mfma_f32_16x16x32_bf16 v[80:83], v[196:199], v[128:131], v[80:83]
	v_mfma_f32_16x16x32_bf16 v[88:91], v[196:199], v[132:135], v[88:91]
	v_mfma_f32_16x16x32_bf16 v[16:19], v[196:199], v[136:139], v[16:19]
	v_mfma_f32_16x16x32_bf16 v[24:27], v[196:199], v[140:143], v[24:27]
	s_waitcnt lgkmcnt(2)
	v_mfma_f32_16x16x32_bf16 v[84:87], v[200:203], v[128:131], v[84:87]
	v_mfma_f32_16x16x32_bf16 v[92:95], v[200:203], v[132:135], v[92:95]
	v_mfma_f32_16x16x32_bf16 v[20:23], v[200:203], v[136:139], v[20:23]
	v_mfma_f32_16x16x32_bf16 v[28:31], v[200:203], v[140:143], v[28:31]
	s_waitcnt lgkmcnt(1)
	v_mfma_f32_16x16x32_bf16 v[64:67], v[204:207], v[128:131], v[64:67]
	v_mfma_f32_16x16x32_bf16 v[72:75], v[204:207], v[132:135], v[72:75]
	v_mfma_f32_16x16x32_bf16 v[0:3], v[204:207], v[136:139], v[0:3]
	v_mfma_f32_16x16x32_bf16 v[8:11], v[204:207], v[140:143], v[8:11]
	s_waitcnt lgkmcnt(0)
	v_mfma_f32_16x16x32_bf16 v[68:71], v[242:245], v[128:131], v[68:71]
	v_mfma_f32_16x16x32_bf16 v[76:79], v[242:245], v[132:135], v[76:79]
	v_mfma_f32_16x16x32_bf16 v[4:7], v[242:245], v[136:139], v[4:7]
	v_mfma_f32_16x16x32_bf16 v[12:15], v[242:245], v[140:143], v[12:15]
	global_load_dwordx4 v[128:131], v[248:249], off
	global_load_dwordx4 v[132:135], v[248:249], off offset:256
	global_load_dwordx4 v[136:139], v[250:251], off
	global_load_dwordx4 v[140:143], v[250:251], off offset:256
	s_waitcnt vmcnt(10)
	s_barrier
	s_add_i32 s9, s3, 7
	s_lshl_b32 s96, s9, 13
	s_add_i32 m0, vcc_lo, 8192
	v_lshl_add_u64 v[160:161], v[188:189], 0, s[96:97]
	global_load_lds_dwordx4 v[160:161], off
	global_load_lds_dwordx4 v[160:161], off offset:1024
	ds_read_b128 v[196:199], v246 offset:16384
	ds_read_b128 v[200:203], v162 offset:16384
	ds_read_b128 v[204:207], v246 offset:18432
	ds_read_b128 v[242:245], v162 offset:18432
	s_add_i32 s9, s3, 7
	s_lshl_b32 s96, s9, 11
	v_lshl_add_u64 v[248:249], v[184:185], 0, s[96:97]
	v_lshl_add_u64 v[250:251], v[186:187], 0, s[96:97]
	s_waitcnt vmcnt(8) lgkmcnt(3)
	v_mfma_f32_16x16x32_bf16 v[112:115], v[196:199], v[144:147], v[112:115]
	v_mfma_f32_16x16x32_bf16 v[120:123], v[196:199], v[148:151], v[120:123]
	v_mfma_f32_16x16x32_bf16 v[48:51], v[196:199], v[152:155], v[48:51]
	v_mfma_f32_16x16x32_bf16 v[56:59], v[196:199], v[156:159], v[56:59]
	ds_read_b128 v[196:199], v246 offset:20480
	s_waitcnt lgkmcnt(3)
	v_mfma_f32_16x16x32_bf16 v[116:119], v[200:203], v[144:147], v[116:119]
	v_mfma_f32_16x16x32_bf16 v[124:127], v[200:203], v[148:151], v[124:127]
	v_mfma_f32_16x16x32_bf16 v[52:55], v[200:203], v[152:155], v[52:55]
	v_mfma_f32_16x16x32_bf16 v[60:63], v[200:203], v[156:159], v[60:63]
	ds_read_b128 v[200:203], v162 offset:20480
	s_waitcnt lgkmcnt(3)
	v_mfma_f32_16x16x32_bf16 v[96:99], v[204:207], v[144:147], v[96:99]
	v_mfma_f32_16x16x32_bf16 v[104:107], v[204:207], v[148:151], v[104:107]
	v_mfma_f32_16x16x32_bf16 v[32:35], v[204:207], v[152:155], v[32:35]
	v_mfma_f32_16x16x32_bf16 v[40:43], v[204:207], v[156:159], v[40:43]
	ds_read_b128 v[204:207], v246 offset:22528
	s_waitcnt lgkmcnt(3)
	v_mfma_f32_16x16x32_bf16 v[100:103], v[242:245], v[144:147], v[100:103]
	v_mfma_f32_16x16x32_bf16 v[108:111], v[242:245], v[148:151], v[108:111]
	v_mfma_f32_16x16x32_bf16 v[36:39], v[242:245], v[152:155], v[36:39]
	v_mfma_f32_16x16x32_bf16 v[44:47], v[242:245], v[156:159], v[44:47]
	ds_read_b128 v[242:245], v162 offset:22528
	s_waitcnt lgkmcnt(3)
	v_mfma_f32_16x16x32_bf16 v[80:83], v[196:199], v[144:147], v[80:83]
	v_mfma_f32_16x16x32_bf16 v[88:91], v[196:199], v[148:151], v[88:91]
	v_mfma_f32_16x16x32_bf16 v[16:19], v[196:199], v[152:155], v[16:19]
	v_mfma_f32_16x16x32_bf16 v[24:27], v[196:199], v[156:159], v[24:27]
	s_waitcnt lgkmcnt(2)
	v_mfma_f32_16x16x32_bf16 v[84:87], v[200:203], v[144:147], v[84:87]
	v_mfma_f32_16x16x32_bf16 v[92:95], v[200:203], v[148:151], v[92:95]
	v_mfma_f32_16x16x32_bf16 v[20:23], v[200:203], v[152:155], v[20:23]
	v_mfma_f32_16x16x32_bf16 v[28:31], v[200:203], v[156:159], v[28:31]
	s_waitcnt lgkmcnt(1)
	v_mfma_f32_16x16x32_bf16 v[64:67], v[204:207], v[144:147], v[64:67]
	v_mfma_f32_16x16x32_bf16 v[72:75], v[204:207], v[148:151], v[72:75]
	v_mfma_f32_16x16x32_bf16 v[0:3], v[204:207], v[152:155], v[0:3]
	v_mfma_f32_16x16x32_bf16 v[8:11], v[204:207], v[156:159], v[8:11]
	s_waitcnt lgkmcnt(0)
	v_mfma_f32_16x16x32_bf16 v[68:71], v[242:245], v[144:147], v[68:71]
	v_mfma_f32_16x16x32_bf16 v[76:79], v[242:245], v[148:151], v[76:79]
	v_mfma_f32_16x16x32_bf16 v[4:7], v[242:245], v[152:155], v[4:7]
	v_mfma_f32_16x16x32_bf16 v[12:15], v[242:245], v[156:159], v[12:15]
	global_load_dwordx4 v[144:147], v[248:249], off
	global_load_dwordx4 v[148:151], v[248:249], off offset:256
	global_load_dwordx4 v[152:155], v[250:251], off
	global_load_dwordx4 v[156:159], v[250:251], off offset:256
	s_waitcnt vmcnt(10)
	s_barrier
	s_add_i32 s3, s3, 6
	s_cmp_lt_u32 s3, 30
	s_cbranch_scc1 .Lg16_out_k
	ds_read_b128 v[196:199], v246 offset:0
	ds_read_b128 v[200:203], v162 offset:0
	ds_read_b128 v[204:207], v246 offset:2048
	ds_read_b128 v[242:245], v162 offset:2048
	s_waitcnt vmcnt(6) lgkmcnt(3)
	v_mfma_f32_16x16x32_bf16 v[112:115], v[196:199], v[128:131], v[112:115]
	v_mfma_f32_16x16x32_bf16 v[120:123], v[196:199], v[132:135], v[120:123]
	v_mfma_f32_16x16x32_bf16 v[48:51], v[196:199], v[136:139], v[48:51]
	v_mfma_f32_16x16x32_bf16 v[56:59], v[196:199], v[140:143], v[56:59]
	ds_read_b128 v[196:199], v246 offset:4096
	s_waitcnt lgkmcnt(3)
	v_mfma_f32_16x16x32_bf16 v[116:119], v[200:203], v[128:131], v[116:119]
	v_mfma_f32_16x16x32_bf16 v[124:127], v[200:203], v[132:135], v[124:127]
	v_mfma_f32_16x16x32_bf16 v[52:55], v[200:203], v[136:139], v[52:55]
	v_mfma_f32_16x16x32_bf16 v[60:63], v[200:203], v[140:143], v[60:63]
	ds_read_b128 v[200:203], v162 offset:4096
	s_waitcnt lgkmcnt(3)
	v_mfma_f32_16x16x32_bf16 v[96:99], v[204:207], v[128:131], v[96:99]
	v_mfma_f32_16x16x32_bf16 v[104:107], v[204:207], v[132:135], v[104:107]
	v_mfma_f32_16x16x32_bf16 v[32:35], v[204:207], v[136:139], v[32:35]
	v_mfma_f32_16x16x32_bf16 v[40:43], v[204:207], v[140:143], v[40:43]
	ds_read_b128 v[204:207], v246 offset:6144
	s_waitcnt lgkmcnt(3)
	v_mfma_f32_16x16x32_bf16 v[100:103], v[242:245], v[128:131], v[100:103]
	v_mfma_f32_16x16x32_bf16 v[108:111], v[242:245], v[132:135], v[108:111]
	v_mfma_f32_16x16x32_bf16 v[36:39], v[242:245], v[136:139], v[36:39]
	v_mfma_f32_16x16x32_bf16 v[44:47], v[242:245], v[140:143], v[44:47]
	ds_read_b128 v[242:245], v162 offset:6144
	s_waitcnt lgkmcnt(3)
	v_mfma_f32_16x16x32_bf16 v[80:83], v[196:199], v[128:131], v[80:83]
	v_mfma_f32_16x16x32_bf16 v[88:91], v[196:199], v[132:135], v[88:91]
	v_mfma_f32_16x16x32_bf16 v[16:19], v[196:199], v[136:139], v[16:19]
	v_mfma_f32_16x16x32_bf16 v[24:27], v[196:199], v[140:143], v[24:27]
	s_waitcnt lgkmcnt(2)
	v_mfma_f32_16x16x32_bf16 v[84:87], v[200:203], v[128:131], v[84:87]
	v_mfma_f32_16x16x32_bf16 v[92:95], v[200:203], v[132:135], v[92:95]
	v_mfma_f32_16x16x32_bf16 v[20:23], v[200:203], v[136:139], v[20:23]
	v_mfma_f32_16x16x32_bf16 v[28:31], v[200:203], v[140:143], v[28:31]
	s_waitcnt lgkmcnt(1)
	v_mfma_f32_16x16x32_bf16 v[64:67], v[204:207], v[128:131], v[64:67]
	v_mfma_f32_16x16x32_bf16 v[72:75], v[204:207], v[132:135], v[72:75]
	v_mfma_f32_16x16x32_bf16 v[0:3], v[204:207], v[136:139], v[0:3]
	v_mfma_f32_16x16x32_bf16 v[8:11], v[204:207], v[140:143], v[8:11]
	s_waitcnt lgkmcnt(0)
	v_mfma_f32_16x16x32_bf16 v[68:71], v[242:245], v[128:131], v[68:71]
	v_mfma_f32_16x16x32_bf16 v[76:79], v[242:245], v[132:135], v[76:79]
	v_mfma_f32_16x16x32_bf16 v[4:7], v[242:245], v[136:139], v[4:7]
	v_mfma_f32_16x16x32_bf16 v[12:15], v[242:245], v[140:143], v[12:15]
	s_waitcnt vmcnt(4)
	s_barrier
	ds_read_b128 v[196:199], v246 offset:8192
	ds_read_b128 v[200:203], v162 offset:8192
	ds_read_b128 v[204:207], v246 offset:10240
	ds_read_b128 v[242:245], v162 offset:10240
	s_waitcnt vmcnt(0) lgkmcnt(3)
	v_mfma_f32_16x16x32_bf16 v[112:115], v[196:199], v[144:147], v[112:115]
	v_mfma_f32_16x16x32_bf16 v[120:123], v[196:199], v[148:151], v[120:123]
	v_mfma_f32_16x16x32_bf16 v[48:51], v[196:199], v[152:155], v[48:51]
	v_mfma_f32_16x16x32_bf16 v[56:59], v[196:199], v[156:159], v[56:59]
	ds_read_b128 v[196:199], v246 offset:12288
	s_waitcnt lgkmcnt(3)
	v_mfma_f32_16x16x32_bf16 v[116:119], v[200:203], v[144:147], v[116:119]
	v_mfma_f32_16x16x32_bf16 v[124:127], v[200:203], v[148:151], v[124:127]
	v_mfma_f32_16x16x32_bf16 v[52:55], v[200:203], v[152:155], v[52:55]
	v_mfma_f32_16x16x32_bf16 v[60:63], v[200:203], v[156:159], v[60:63]
	ds_read_b128 v[200:203], v162 offset:12288
	s_waitcnt lgkmcnt(3)
	v_mfma_f32_16x16x32_bf16 v[96:99], v[204:207], v[144:147], v[96:99]
	v_mfma_f32_16x16x32_bf16 v[104:107], v[204:207], v[148:151], v[104:107]
	v_mfma_f32_16x16x32_bf16 v[32:35], v[204:207], v[152:155], v[32:35]
	v_mfma_f32_16x16x32_bf16 v[40:43], v[204:207], v[156:159], v[40:43]
	ds_read_b128 v[204:207], v246 offset:14336
	s_waitcnt lgkmcnt(3)
	v_mfma_f32_16x16x32_bf16 v[100:103], v[242:245], v[144:147], v[100:103]
	v_mfma_f32_16x16x32_bf16 v[108:111], v[242:245], v[148:151], v[108:111]
	v_mfma_f32_16x16x32_bf16 v[36:39], v[242:245], v[152:155], v[36:39]
	v_mfma_f32_16x16x32_bf16 v[44:47], v[242:245], v[156:159], v[44:47]
	ds_read_b128 v[242:245], v162 offset:14336
	s_waitcnt lgkmcnt(3)
	v_mfma_f32_16x16x32_bf16 v[80:83], v[196:199], v[144:147], v[80:83]
	v_mfma_f32_16x16x32_bf16 v[88:91], v[196:199], v[148:151], v[88:91]
	v_mfma_f32_16x16x32_bf16 v[16:19], v[196:199], v[152:155], v[16:19]
	v_mfma_f32_16x16x32_bf16 v[24:27], v[196:199], v[156:159], v[24:27]
	s_waitcnt lgkmcnt(2)
	v_mfma_f32_16x16x32_bf16 v[84:87], v[200:203], v[144:147], v[84:87]
	v_mfma_f32_16x16x32_bf16 v[92:95], v[200:203], v[148:151], v[92:95]
	v_mfma_f32_16x16x32_bf16 v[20:23], v[200:203], v[152:155], v[20:23]
	v_mfma_f32_16x16x32_bf16 v[28:31], v[200:203], v[156:159], v[28:31]
	s_waitcnt lgkmcnt(1)
	v_mfma_f32_16x16x32_bf16 v[64:67], v[204:207], v[144:147], v[64:67]
	v_mfma_f32_16x16x32_bf16 v[72:75], v[204:207], v[148:151], v[72:75]
	v_mfma_f32_16x16x32_bf16 v[0:3], v[204:207], v[152:155], v[0:3]
	v_mfma_f32_16x16x32_bf16 v[8:11], v[204:207], v[156:159], v[8:11]
	s_waitcnt lgkmcnt(0)
	v_mfma_f32_16x16x32_bf16 v[68:71], v[242:245], v[144:147], v[68:71]
	v_mfma_f32_16x16x32_bf16 v[76:79], v[242:245], v[148:151], v[76:79]
	v_mfma_f32_16x16x32_bf16 v[4:7], v[242:245], v[152:155], v[4:7]
	v_mfma_f32_16x16x32_bf16 v[12:15], v[242:245], v[156:159], v[12:15]
	s_barrier
	s_nop 0
	s_nop 7
	s_nop 1
	s_waitcnt vmcnt(0)
	s_waitcnt vmcnt(0)
	v_and_b32_e32 v188, 63, v179
	v_lshrrev_b32_e32 v189, 6, v179
	v_mul_u32_u24_e32 v249, 0x2400, v189
	v_mov_b32_e32 v250, v249
	v_and_b32_e32 v251, 15, v188
	v_mul_u32_u24_e32 v251, 0x110, v251
	v_add_u32_e32 v249, v249, v251
	v_lshrrev_b32_e32 v251, 4, v188
	v_lshl_add_u32 v249, v251, 5, v249
	v_lshrrev_b32_e32 v237, 4, v188
	v_mul_u32_u24_e32 v251, 0x110, v237
	v_add_u32_e32 v250, v250, v251
	v_and_b32_e32 v251, 15, v188
	v_lshlrev_b32_e32 v251, 4, v251
	v_add_u32_e32 v250, v250, v251
	v_lshl_add_u32 v237, v189, 6, v237
	v_lshl_add_u32 v237, v237, 12, v251
	v_add_u32_e32 v238, 16384, v237
	v_add_u32_e32 v239, 32768, v237
	v_add_u32_e32 v240, 49152, v237
	v_add_u32_e32 v241, 65536, v237
	v_add_u32_e32 v242, 81920, v237
	v_add_u32_e32 v243, 98304, v237
	v_add_u32_e32 v248, 114688, v237
	s_lshl_b32 s16, s8, 8
	s_lshl_b32 s18, s2, 9
	s_lshr_b32 s19, s8, 4
	v_readlane_b32 s12, v254, 38
	v_readlane_b32 s13, v254, 37
	v_readlane_b32 s14, v253, 46
	v_readlane_b32 s15, v253, 47
	v_readlane_b32 s22, v254, 40
	v_readlane_b32 s23, v254, 39
	s_add_i32 s17, s16, 0xffff8000
	s_cmpk_lt_u32 s8, 0x80
	s_cselect_b32 s12, s12, s22
	s_cselect_b32 s13, s13, s23
	s_cselect_b32 s14, s14, s62
	s_cselect_b32 s15, s15, s63
	s_cselect_b32 s19, s19, 8
	s_cselect_b32 s16, s16, s17
	s_mov_b32 s17, 0
	s_lshl_b64 s[16:17], s[16:17], 12
	s_add_u32 s16, s16, s18
	s_addc_u32 s17, s17, 0
	s_add_u32 s12, s12, s16
	s_addc_u32 s13, s13, s17
	s_add_u32 s14, s14, s16
	s_addc_u32 s15, s15, s17
	s_mul_i32 s19, s19, 0x6000
	s_add_u32 s20, s0, s19
	s_addc_u32 s21, s1, 0
	s_add_u32 s20, s20, s18
	s_addc_u32 s21, s21, 0
	global_load_dwordx4 v[244:247], v251, s[20:21]
	global_load_dwordx4 v[160:163], v237, s[12:13]
	global_load_dwordx4 v[164:167], v238, s[12:13]
	global_load_dwordx4 v[168:171], v239, s[12:13]
	global_load_dwordx4 v[172:175], v240, s[12:13]
	global_load_dwordx4 v[196:199], v241, s[12:13]
	global_load_dwordx4 v[200:203], v242, s[12:13]
	global_load_dwordx4 v[204:207], v243, s[12:13]
	global_load_dwordx4 v[184:187], v248, s[12:13]
	ds_write_b128 v249, v[112:115]
	ds_write_b128 v249, v[116:119] offset:16
	ds_write_b128 v249, v[96:99] offset:128
	ds_write_b128 v249, v[100:103] offset:144
	ds_write_b128 v249, v[120:123] offset:4352
	ds_write_b128 v249, v[124:127] offset:4368
	ds_write_b128 v249, v[104:107] offset:4480
	ds_write_b128 v249, v[108:111] offset:4496
	s_waitcnt lgkmcnt(0)
	ds_read_b128 v[128:131], v250
	ds_read_b128 v[132:135], v250 offset:1088
	ds_read_b128 v[136:139], v250 offset:2176
	ds_read_b128 v[140:143], v250 offset:3264
	ds_read_b128 v[144:147], v250 offset:4352
	ds_read_b128 v[148:151], v250 offset:5440
	ds_read_b128 v[152:155], v250 offset:6528
	ds_read_b128 v[156:159], v250 offset:7616
	s_waitcnt vmcnt(7) lgkmcnt(7)
	v_fma_f32 v128, v244, v128, v160
	v_fma_f32 v129, v245, v129, v161
	v_fma_f32 v130, v246, v130, v162
	v_fma_f32 v131, v247, v131, v163
	global_store_dwordx4 v237, v[128:131], s[14:15] sc0 sc1
	s_waitcnt vmcnt(7) lgkmcnt(6)
	v_fma_f32 v132, v244, v132, v164
	v_fma_f32 v133, v245, v133, v165
	v_fma_f32 v134, v246, v134, v166
	v_fma_f32 v135, v247, v135, v167
	global_store_dwordx4 v238, v[132:135], s[14:15] sc0 sc1
	s_waitcnt vmcnt(7) lgkmcnt(5)
	v_fma_f32 v136, v244, v136, v168
	v_fma_f32 v137, v245, v137, v169
	v_fma_f32 v138, v246, v138, v170
	v_fma_f32 v139, v247, v139, v171
	global_store_dwordx4 v239, v[136:139], s[14:15] sc0 sc1
	s_waitcnt vmcnt(7) lgkmcnt(4)
	v_fma_f32 v140, v244, v140, v172
	v_fma_f32 v141, v245, v141, v173
	v_fma_f32 v142, v246, v142, v174
	v_fma_f32 v143, v247, v143, v175
	global_store_dwordx4 v240, v[140:143], s[14:15] sc0 sc1
	s_waitcnt vmcnt(7) lgkmcnt(3)
	v_fma_f32 v144, v244, v144, v196
	v_fma_f32 v145, v245, v145, v197
	v_fma_f32 v146, v246, v146, v198
	v_fma_f32 v147, v247, v147, v199
	global_store_dwordx4 v241, v[144:147], s[14:15] sc0 sc1
	s_waitcnt vmcnt(7) lgkmcnt(2)
	v_fma_f32 v148, v244, v148, v200
	v_fma_f32 v149, v245, v149, v201
	v_fma_f32 v150, v246, v150, v202
	v_fma_f32 v151, v247, v151, v203
	global_store_dwordx4 v242, v[148:151], s[14:15] sc0 sc1
	s_waitcnt vmcnt(7) lgkmcnt(1)
	v_fma_f32 v152, v244, v152, v204
	v_fma_f32 v153, v245, v153, v205
	v_fma_f32 v154, v246, v154, v206
	v_fma_f32 v155, v247, v155, v207
	global_store_dwordx4 v243, v[152:155], s[14:15] sc0 sc1
	s_waitcnt vmcnt(7) lgkmcnt(0)
	v_fma_f32 v156, v244, v156, v184
	v_fma_f32 v157, v245, v157, v185
	v_fma_f32 v158, v246, v158, v186
	v_fma_f32 v159, v247, v159, v187
	global_store_dwordx4 v248, v[156:159], s[14:15] sc0 sc1
	global_load_dwordx4 v[244:247], v251, s[20:21] offset:256
	global_load_dwordx4 v[160:163], v237, s[12:13] offset:256
	global_load_dwordx4 v[164:167], v238, s[12:13] offset:256
	global_load_dwordx4 v[168:171], v239, s[12:13] offset:256
	global_load_dwordx4 v[172:175], v240, s[12:13] offset:256
	global_load_dwordx4 v[196:199], v241, s[12:13] offset:256
	global_load_dwordx4 v[200:203], v242, s[12:13] offset:256
	global_load_dwordx4 v[204:207], v243, s[12:13] offset:256
	global_load_dwordx4 v[184:187], v248, s[12:13] offset:256
	ds_write_b128 v249, v[80:83]
	ds_write_b128 v249, v[84:87] offset:16
	ds_write_b128 v249, v[64:67] offset:128
	ds_write_b128 v249, v[68:71] offset:144
	ds_write_b128 v249, v[88:91] offset:4352
	ds_write_b128 v249, v[92:95] offset:4368
	ds_write_b128 v249, v[72:75] offset:4480
	ds_write_b128 v249, v[76:79] offset:4496
	s_waitcnt lgkmcnt(0)
	ds_read_b128 v[128:131], v250
	ds_read_b128 v[132:135], v250 offset:1088
	ds_read_b128 v[136:139], v250 offset:2176
	ds_read_b128 v[140:143], v250 offset:3264
	ds_read_b128 v[144:147], v250 offset:4352
	ds_read_b128 v[148:151], v250 offset:5440
	ds_read_b128 v[152:155], v250 offset:6528
	ds_read_b128 v[156:159], v250 offset:7616
	s_waitcnt vmcnt(7) lgkmcnt(7)
	v_fma_f32 v128, v244, v128, v160
	v_fma_f32 v129, v245, v129, v161
	v_fma_f32 v130, v246, v130, v162
	v_fma_f32 v131, v247, v131, v163
	global_store_dwordx4 v237, v[128:131], s[14:15] offset:256 sc0 sc1
	s_waitcnt vmcnt(7) lgkmcnt(6)
	v_fma_f32 v132, v244, v132, v164
	v_fma_f32 v133, v245, v133, v165
	v_fma_f32 v134, v246, v134, v166
	v_fma_f32 v135, v247, v135, v167
	global_store_dwordx4 v238, v[132:135], s[14:15] offset:256 sc0 sc1
	s_waitcnt vmcnt(7) lgkmcnt(5)
	v_fma_f32 v136, v244, v136, v168
	v_fma_f32 v137, v245, v137, v169
	v_fma_f32 v138, v246, v138, v170
	v_fma_f32 v139, v247, v139, v171
	global_store_dwordx4 v239, v[136:139], s[14:15] offset:256 sc0 sc1
	s_waitcnt vmcnt(7) lgkmcnt(4)
	v_fma_f32 v140, v244, v140, v172
	v_fma_f32 v141, v245, v141, v173
	v_fma_f32 v142, v246, v142, v174
	v_fma_f32 v143, v247, v143, v175
	global_store_dwordx4 v240, v[140:143], s[14:15] offset:256 sc0 sc1
	s_waitcnt vmcnt(7) lgkmcnt(3)
	v_fma_f32 v144, v244, v144, v196
	v_fma_f32 v145, v245, v145, v197
	v_fma_f32 v146, v246, v146, v198
	v_fma_f32 v147, v247, v147, v199
	global_store_dwordx4 v241, v[144:147], s[14:15] offset:256 sc0 sc1
	s_waitcnt vmcnt(7) lgkmcnt(2)
	v_fma_f32 v148, v244, v148, v200
	v_fma_f32 v149, v245, v149, v201
	v_fma_f32 v150, v246, v150, v202
	v_fma_f32 v151, v247, v151, v203
	global_store_dwordx4 v242, v[148:151], s[14:15] offset:256 sc0 sc1
	s_waitcnt vmcnt(7) lgkmcnt(1)
	v_fma_f32 v152, v244, v152, v204
	v_fma_f32 v153, v245, v153, v205
	v_fma_f32 v154, v246, v154, v206
	v_fma_f32 v155, v247, v155, v207
	global_store_dwordx4 v243, v[152:155], s[14:15] offset:256 sc0 sc1
	s_waitcnt vmcnt(7) lgkmcnt(0)
	v_fma_f32 v156, v244, v156, v184
	v_fma_f32 v157, v245, v157, v185
	v_fma_f32 v158, v246, v158, v186
	v_fma_f32 v159, v247, v159, v187
	global_store_dwordx4 v248, v[156:159], s[14:15] offset:256 sc0 sc1
	s_add_u32 s12, s12, 0x20000
	s_addc_u32 s13, s13, 0
	s_add_u32 s14, s14, 0x20000
	s_addc_u32 s15, s15, 0
	global_load_dwordx4 v[244:247], v251, s[20:21]
	global_load_dwordx4 v[160:163], v237, s[12:13]
	global_load_dwordx4 v[164:167], v238, s[12:13]
	global_load_dwordx4 v[168:171], v239, s[12:13]
	global_load_dwordx4 v[172:175], v240, s[12:13]
	global_load_dwordx4 v[196:199], v241, s[12:13]
	global_load_dwordx4 v[200:203], v242, s[12:13]
	global_load_dwordx4 v[204:207], v243, s[12:13]
	global_load_dwordx4 v[184:187], v248, s[12:13]
	ds_write_b128 v249, v[48:51]
	ds_write_b128 v249, v[52:55] offset:16
	ds_write_b128 v249, v[32:35] offset:128
	ds_write_b128 v249, v[36:39] offset:144
	ds_write_b128 v249, v[56:59] offset:4352
	ds_write_b128 v249, v[60:63] offset:4368
	ds_write_b128 v249, v[40:43] offset:4480
	ds_write_b128 v249, v[44:47] offset:4496
	s_waitcnt lgkmcnt(0)
	ds_read_b128 v[128:131], v250
	ds_read_b128 v[132:135], v250 offset:1088
	ds_read_b128 v[136:139], v250 offset:2176
	ds_read_b128 v[140:143], v250 offset:3264
	ds_read_b128 v[144:147], v250 offset:4352
	ds_read_b128 v[148:151], v250 offset:5440
	ds_read_b128 v[152:155], v250 offset:6528
	ds_read_b128 v[156:159], v250 offset:7616
	s_waitcnt vmcnt(7) lgkmcnt(7)
	v_fma_f32 v128, v244, v128, v160
	v_fma_f32 v129, v245, v129, v161
	v_fma_f32 v130, v246, v130, v162
	v_fma_f32 v131, v247, v131, v163
	global_store_dwordx4 v237, v[128:131], s[14:15] sc0 sc1
	s_waitcnt vmcnt(7) lgkmcnt(6)
	v_fma_f32 v132, v244, v132, v164
	v_fma_f32 v133, v245, v133, v165
	v_fma_f32 v134, v246, v134, v166
	v_fma_f32 v135, v247, v135, v167
	global_store_dwordx4 v238, v[132:135], s[14:15] sc0 sc1
	s_waitcnt vmcnt(7) lgkmcnt(5)
	v_fma_f32 v136, v244, v136, v168
	v_fma_f32 v137, v245, v137, v169
	v_fma_f32 v138, v246, v138, v170
	v_fma_f32 v139, v247, v139, v171
	global_store_dwordx4 v239, v[136:139], s[14:15] sc0 sc1
	s_waitcnt vmcnt(7) lgkmcnt(4)
	v_fma_f32 v140, v244, v140, v172
	v_fma_f32 v141, v245, v141, v173
	v_fma_f32 v142, v246, v142, v174
	v_fma_f32 v143, v247, v143, v175
	global_store_dwordx4 v240, v[140:143], s[14:15] sc0 sc1
	s_waitcnt vmcnt(7) lgkmcnt(3)
	v_fma_f32 v144, v244, v144, v196
	v_fma_f32 v145, v245, v145, v197
	v_fma_f32 v146, v246, v146, v198
	v_fma_f32 v147, v247, v147, v199
	global_store_dwordx4 v241, v[144:147], s[14:15] sc0 sc1
	s_waitcnt vmcnt(7) lgkmcnt(2)
	v_fma_f32 v148, v244, v148, v200
	v_fma_f32 v149, v245, v149, v201
	v_fma_f32 v150, v246, v150, v202
	v_fma_f32 v151, v247, v151, v203
	global_store_dwordx4 v242, v[148:151], s[14:15] sc0 sc1
	s_waitcnt vmcnt(7) lgkmcnt(1)
	v_fma_f32 v152, v244, v152, v204
	v_fma_f32 v153, v245, v153, v205
	v_fma_f32 v154, v246, v154, v206
	v_fma_f32 v155, v247, v155, v207
	global_store_dwordx4 v243, v[152:155], s[14:15] sc0 sc1
	s_waitcnt vmcnt(7) lgkmcnt(0)
	v_fma_f32 v156, v244, v156, v184
	v_fma_f32 v157, v245, v157, v185
	v_fma_f32 v158, v246, v158, v186
	v_fma_f32 v159, v247, v159, v187
	global_store_dwordx4 v248, v[156:159], s[14:15] sc0 sc1
	global_load_dwordx4 v[244:247], v251, s[20:21] offset:256
	global_load_dwordx4 v[160:163], v237, s[12:13] offset:256
	global_load_dwordx4 v[164:167], v238, s[12:13] offset:256
	global_load_dwordx4 v[168:171], v239, s[12:13] offset:256
	global_load_dwordx4 v[172:175], v240, s[12:13] offset:256
	global_load_dwordx4 v[196:199], v241, s[12:13] offset:256
	global_load_dwordx4 v[200:203], v242, s[12:13] offset:256
	global_load_dwordx4 v[204:207], v243, s[12:13] offset:256
	global_load_dwordx4 v[184:187], v248, s[12:13] offset:256
	ds_write_b128 v249, v[16:19]
	ds_write_b128 v249, v[20:23] offset:16
	ds_write_b128 v249, v[0:3] offset:128
	ds_write_b128 v249, v[4:7] offset:144
	ds_write_b128 v249, v[24:27] offset:4352
	ds_write_b128 v249, v[28:31] offset:4368
	ds_write_b128 v249, v[8:11] offset:4480
	ds_write_b128 v249, v[12:15] offset:4496
	s_waitcnt lgkmcnt(0)
	ds_read_b128 v[128:131], v250
	ds_read_b128 v[132:135], v250 offset:1088
	ds_read_b128 v[136:139], v250 offset:2176
	ds_read_b128 v[140:143], v250 offset:3264
	ds_read_b128 v[144:147], v250 offset:4352
	ds_read_b128 v[148:151], v250 offset:5440
	ds_read_b128 v[152:155], v250 offset:6528
	ds_read_b128 v[156:159], v250 offset:7616
	s_waitcnt vmcnt(7) lgkmcnt(7)
	v_fma_f32 v128, v244, v128, v160
	v_fma_f32 v129, v245, v129, v161
	v_fma_f32 v130, v246, v130, v162
	v_fma_f32 v131, v247, v131, v163
	global_store_dwordx4 v237, v[128:131], s[14:15] offset:256 sc0 sc1
	s_waitcnt vmcnt(7) lgkmcnt(6)
	v_fma_f32 v132, v244, v132, v164
	v_fma_f32 v133, v245, v133, v165
	v_fma_f32 v134, v246, v134, v166
	v_fma_f32 v135, v247, v135, v167
	global_store_dwordx4 v238, v[132:135], s[14:15] offset:256 sc0 sc1
	s_waitcnt vmcnt(7) lgkmcnt(5)
	v_fma_f32 v136, v244, v136, v168
	v_fma_f32 v137, v245, v137, v169
	v_fma_f32 v138, v246, v138, v170
	v_fma_f32 v139, v247, v139, v171
	global_store_dwordx4 v239, v[136:139], s[14:15] offset:256 sc0 sc1
	s_waitcnt vmcnt(7) lgkmcnt(4)
	v_fma_f32 v140, v244, v140, v172
	v_fma_f32 v141, v245, v141, v173
	v_fma_f32 v142, v246, v142, v174
	v_fma_f32 v143, v247, v143, v175
	global_store_dwordx4 v240, v[140:143], s[14:15] offset:256 sc0 sc1
	s_waitcnt vmcnt(7) lgkmcnt(3)
	v_fma_f32 v144, v244, v144, v196
	v_fma_f32 v145, v245, v145, v197
	v_fma_f32 v146, v246, v146, v198
	v_fma_f32 v147, v247, v147, v199
	global_store_dwordx4 v241, v[144:147], s[14:15] offset:256 sc0 sc1
	s_waitcnt vmcnt(7) lgkmcnt(2)
	v_fma_f32 v148, v244, v148, v200
	v_fma_f32 v149, v245, v149, v201
	v_fma_f32 v150, v246, v150, v202
	v_fma_f32 v151, v247, v151, v203
	global_store_dwordx4 v242, v[148:151], s[14:15] offset:256 sc0 sc1
	s_waitcnt vmcnt(7) lgkmcnt(1)
	v_fma_f32 v152, v244, v152, v204
	v_fma_f32 v153, v245, v153, v205
	v_fma_f32 v154, v246, v154, v206
	v_fma_f32 v155, v247, v155, v207
	global_store_dwordx4 v243, v[152:155], s[14:15] offset:256 sc0 sc1
	s_waitcnt vmcnt(7) lgkmcnt(0)
	v_fma_f32 v156, v244, v156, v184
	v_fma_f32 v157, v245, v157, v185
	v_fma_f32 v158, v246, v158, v186
	v_fma_f32 v159, v247, v159, v187
	global_store_dwordx4 v248, v[156:159], s[14:15] offset:256 sc0 sc1
	s_waitcnt lgkmcnt(0)
	v_readlane_b32 s16, v254, 11
	s_andn2_b32 s17, s26, 63
	s_add_i32 s4, s4, s16
	s_cmp_lt_i32 s4, s17
	s_cbranch_scc0 .Lhx_out_left
	s_barrier
	s_branch .LBB0_923

.LBB0_1086:
	s_ashr_i32 s6, s2, 31
	s_lshr_b32 s6, s6, 26
	s_add_i32 s6, s2, s6
	s_ashr_i32 s7, s6, 6
	s_lshl_b32 s7, s7, 3
	s_sub_i32 s8, s25, s7
	s_min_i32 s8, s8, 8
	s_abs_i32 s9, s8
	v_cvt_f32_u32_e32 v0, s9
	s_sub_i32 s12, 0, s9
	s_andn2_b32 s6, s6, 63
	s_sub_i32 s10, s2, s6
	v_rcp_iflag_f32_e32 v0, v0
	s_abs_i32 s6, s10
	s_xor_b32 s11, s10, s8
	s_ashr_i32 s11, s11, 31
	v_mul_f32_e32 v0, 0x4f7ffffe, v0
	v_cvt_u32_f32_e32 v0, v0
	v_mov_b32_e32 v181, v179
	v_readfirstlane_b32 s13, v0
	s_mul_i32 s12, s12, s13
	s_mul_hi_u32 s12, s13, s12
	s_add_i32 s13, s13, s12
	s_mul_hi_u32 s12, s6, s13
	s_mul_i32 s13, s12, s9
	s_sub_i32 s6, s6, s13
	s_add_i32 s14, s12, 1
	s_sub_i32 s13, s6, s9
	s_cmp_ge_u32 s6, s9
	s_cselect_b32 s12, s14, s12
	s_cselect_b32 s6, s13, s6
	s_add_i32 s13, s12, 1
	s_cmp_ge_u32 s6, s9
	s_cselect_b32 s6, s13, s12
	s_xor_b32 s6, s6, s11
	s_sub_i32 s6, s6, s11
	s_mul_i32 s8, s8, s6
	s_add_i32 s7, s7, s5
	s_sub_i32 s8, s10, s8
	v_ashrrev_i32_e32 v237, 6, v181
	s_add_i32 s7, s7, s8
	v_lshlrev_b32_e32 v0, 1, v237
	v_bfe_u32 v183, v181, 5, 1
	v_lshl_add_u32 v2, s7, 3, v0
	v_mov_b64_e32 v[0:1], s[66:67]
	v_and_b32_e32 v238, 31, v181
	v_mad_i64_i32 v[0:1], s[8:9], v2, s24, v[0:1]
	v_lshlrev_b32_e32 v176, 9, v183
	v_lshl_add_u64 v[0:1], v[0:1], 0, v[176:177]
	v_lshlrev_b32_e32 v176, 4, v238
	v_ashrrev_i32_e32 v38, 2, v181
	s_mul_i32 s8, s6, 0xb0000
	v_lshl_add_u64 v[184:185], v[0:1], 0, v[176:177]
	s_mul_hi_i32 s9, s6, 0xb0000
	s_add_u32 s8, s3, s8
	v_lshlrev_b32_e32 v0, 5, v38
	s_addc_u32 s9, s4, s9
	v_ashrrev_i32_e32 v1, 31, v0
	v_lshlrev_b32_e32 v2, 4, v181
	v_lshl_add_u64 v[0:1], v[0:1], 1, s[8:9]
	v_and_b32_e32 v176, 48, v2
	v_lshl_add_u64 v[186:187], v[0:1], 0, v[176:177]
	s_movk_i32 s8, 0x2000
	v_add_co_u32_e32 v34, vcc, s8, v186
	v_mul_u32_u24_e32 v36, 40, v238
	s_nop 0
	v_addc_co_u32_e32 v35, vcc, 0, v187, vcc
	v_lshlrev_b32_e32 v37, 4, v183
	v_lshl_add_u32 v240, v36, 1, v37
	v_add_co_u32_e32 v36, vcc, s24, v184
	s_movk_i32 s9, 0x50
	s_nop 0
	v_addc_co_u32_e32 v37, vcc, 0, v185, vcc
	v_and_b32_e32 v239, 63, v181
	s_cmp_eq_u32 s100, 1
	s_cbranch_scc1 .Lhx_down_half
	v_bfe_u32 v247, v181, 4, 2
	v_lshlrev_b32_e32 v247, 1, v247
	v_mov_b32_e32 v176, 0x78
	v_lshrrev_b32_e32 v247, v247, v176
	v_and_b32_e32 v247, 3, v247
	v_and_b32_e32 v246, 3, v181
	v_xor_b32_e32 v247, v247, v246
	v_lshlrev_b32_e32 v247, 4, v247
	v_and_b32_e32 v188, 0xffffffcf, v186
	v_or_b32_e32 v188, v188, v247
	v_mov_b32_e32 v189, v187
	v_lshrrev_b32_e32 v176, 6, v181
	v_lshlrev_b32_e32 v247, 11, v176
	v_lshlrev_b32_e32 v176, 10, v176
	v_lshl_add_u64 v[188:189], v[188:189], 0, v[176:177]
	v_readfirstlane_b32 vcc_lo, v247
	v_bfe_u32 v247, v181, 4, 1
	v_lshlrev_b32_e32 v176, 9, v183
	v_lshl_add_u32 v176, v247, 8, v176
	v_lshl_add_u64 v[184:185], v[184:185], 0, v[176:177]
	v_mov_b32_e32 v176, s24
	v_lshl_add_u64 v[186:187], v[184:185], 0, v[176:177]
	v_mov_b32_e32 v176, 0x78
	v_bfe_u32 v247, v181, 2, 1
	v_lshlrev_b32_e32 v247, 2, v247
	v_lshrrev_b32_e32 v247, v247, v176
	v_and_b32_e32 v247, 3, v247
	v_bfe_u32 v246, v181, 4, 2
	v_xor_b32_e32 v247, v247, v246
	v_lshlrev_b32_e32 v247, 4, v247
	v_bfe_u32 v246, v181, 2, 2
	v_lshlrev_b32_e32 v246, 3, v246
	v_and_b32_e32 v162, 3, v181
	v_add_u32_e32 v246, v246, v162
	v_lshl_add_u32 v246, v246, 6, v247
	v_bfe_u32 v247, v181, 2, 1
	v_lshlrev_b32_e32 v247, 2, v247
	v_add_u32_e32 v247, 2, v247
	v_lshrrev_b32_e32 v247, v247, v176
	v_and_b32_e32 v247, 3, v247
	v_bfe_u32 v162, v181, 4, 2
	v_xor_b32_e32 v247, v247, v162
	v_lshlrev_b32_e32 v247, 4, v247
	v_and_b32_e32 v162, 0xffffffcf, v246
	v_add_u32_e32 v162, 0x100, v162
	v_or_b32_e32 v162, v162, v247
	s_mov_b32 s96, 0
	s_mov_b32 m0, vcc_lo
	v_lshl_add_u64 v[160:161], v[188:189], 0, s[96:97]
	global_load_lds_dwordx4 v[160:161], off
	global_load_lds_dwordx4 v[160:161], off offset:1024
	s_mov_b32 s96, 0
	v_lshl_add_u64 v[248:249], v[184:185], 0, s[96:97]
	v_lshl_add_u64 v[250:251], v[186:187], 0, s[96:97]
	global_load_dwordx4 v[128:131], v[248:249], off
	global_load_dwordx4 v[132:135], v[248:249], off offset:256
	global_load_dwordx4 v[136:139], v[250:251], off
	global_load_dwordx4 v[140:143], v[250:251], off offset:256
	s_movk_i32 s96, 0x2000
	s_add_i32 m0, vcc_lo, 8192
	v_lshl_add_u64 v[160:161], v[188:189], 0, s[96:97]
	global_load_lds_dwordx4 v[160:161], off
	global_load_lds_dwordx4 v[160:161], off offset:1024
	s_movk_i32 s96, 0x800
	v_lshl_add_u64 v[248:249], v[184:185], 0, s[96:97]
	v_lshl_add_u64 v[250:251], v[186:187], 0, s[96:97]
	global_load_dwordx4 v[144:147], v[248:249], off
	global_load_dwordx4 v[148:151], v[248:249], off offset:256
	global_load_dwordx4 v[152:155], v[250:251], off
	global_load_dwordx4 v[156:159], v[250:251], off offset:256
	v_mov_b32_e32 v0, 0
	v_mov_b32_e32 v1, 0
	v_mov_b32_e32 v2, 0
	v_mov_b32_e32 v3, 0
	v_mov_b32_e32 v4, 0
	v_mov_b32_e32 v5, 0
	v_mov_b32_e32 v6, 0
	v_mov_b32_e32 v7, 0
	v_mov_b32_e32 v8, 0
	v_mov_b32_e32 v9, 0
	v_mov_b32_e32 v10, 0
	v_mov_b32_e32 v11, 0
	v_mov_b32_e32 v12, 0
	v_mov_b32_e32 v13, 0
	v_mov_b32_e32 v14, 0
	v_mov_b32_e32 v15, 0
	v_mov_b32_e32 v16, 0
	v_mov_b32_e32 v17, 0
	v_mov_b32_e32 v18, 0
	v_mov_b32_e32 v19, 0
	v_mov_b32_e32 v20, 0
	v_mov_b32_e32 v21, 0
	v_mov_b32_e32 v22, 0
	v_mov_b32_e32 v23, 0
	v_mov_b32_e32 v24, 0
	v_mov_b32_e32 v25, 0
	v_mov_b32_e32 v26, 0
	v_mov_b32_e32 v27, 0
	v_mov_b32_e32 v28, 0
	v_mov_b32_e32 v29, 0
	v_mov_b32_e32 v30, 0
	v_mov_b32_e32 v31, 0
	v_mov_b32_e32 v32, 0
	v_mov_b32_e32 v33, 0
	v_mov_b32_e32 v34, 0
	v_mov_b32_e32 v35, 0
	v_mov_b32_e32 v36, 0
	v_mov_b32_e32 v37, 0
	v_mov_b32_e32 v38, 0
	v_mov_b32_e32 v39, 0
	v_mov_b32_e32 v40, 0
	v_mov_b32_e32 v41, 0
	v_mov_b32_e32 v42, 0
	v_mov_b32_e32 v43, 0
	v_mov_b32_e32 v44, 0
	v_mov_b32_e32 v45, 0
	v_mov_b32_e32 v46, 0
	v_mov_b32_e32 v47, 0
	v_mov_b32_e32 v48, 0
	v_mov_b32_e32 v49, 0
	v_mov_b32_e32 v50, 0
	v_mov_b32_e32 v51, 0
	v_mov_b32_e32 v52, 0
	v_mov_b32_e32 v53, 0
	v_mov_b32_e32 v54, 0
	v_mov_b32_e32 v55, 0
	v_mov_b32_e32 v56, 0
	v_mov_b32_e32 v57, 0
	v_mov_b32_e32 v58, 0
	v_mov_b32_e32 v59, 0
	v_mov_b32_e32 v60, 0
	v_mov_b32_e32 v61, 0
	v_mov_b32_e32 v62, 0
	v_mov_b32_e32 v63, 0
	v_mov_b32_e32 v64, 0
	v_mov_b32_e32 v65, 0
	v_mov_b32_e32 v66, 0
	v_mov_b32_e32 v67, 0
	v_mov_b32_e32 v68, 0
	v_mov_b32_e32 v69, 0
	v_mov_b32_e32 v70, 0
	v_mov_b32_e32 v71, 0
	v_mov_b32_e32 v72, 0
	v_mov_b32_e32 v73, 0
	v_mov_b32_e32 v74, 0
	v_mov_b32_e32 v75, 0
	v_mov_b32_e32 v76, 0
	v_mov_b32_e32 v77, 0
	v_mov_b32_e32 v78, 0
	v_mov_b32_e32 v79, 0
	v_mov_b32_e32 v80, 0
	v_mov_b32_e32 v81, 0
	v_mov_b32_e32 v82, 0
	v_mov_b32_e32 v83, 0
	v_mov_b32_e32 v84, 0
	v_mov_b32_e32 v85, 0
	v_mov_b32_e32 v86, 0
	v_mov_b32_e32 v87, 0
	v_mov_b32_e32 v88, 0
	v_mov_b32_e32 v89, 0
	v_mov_b32_e32 v90, 0
	v_mov_b32_e32 v91, 0
	v_mov_b32_e32 v92, 0
	v_mov_b32_e32 v93, 0
	v_mov_b32_e32 v94, 0
	v_mov_b32_e32 v95, 0
	v_mov_b32_e32 v96, 0
	v_mov_b32_e32 v97, 0
	v_mov_b32_e32 v98, 0
	v_mov_b32_e32 v99, 0
	v_mov_b32_e32 v100, 0
	v_mov_b32_e32 v101, 0
	v_mov_b32_e32 v102, 0
	v_mov_b32_e32 v103, 0
	v_mov_b32_e32 v104, 0
	v_mov_b32_e32 v105, 0
	v_mov_b32_e32 v106, 0
	v_mov_b32_e32 v107, 0
	v_mov_b32_e32 v108, 0
	v_mov_b32_e32 v109, 0
	v_mov_b32_e32 v110, 0
	v_mov_b32_e32 v111, 0
	v_mov_b32_e32 v112, 0
	v_mov_b32_e32 v113, 0
	v_mov_b32_e32 v114, 0
	v_mov_b32_e32 v115, 0
	v_mov_b32_e32 v116, 0
	v_mov_b32_e32 v117, 0
	v_mov_b32_e32 v118, 0
	v_mov_b32_e32 v119, 0
	v_mov_b32_e32 v120, 0
	v_mov_b32_e32 v121, 0
	v_mov_b32_e32 v122, 0
	v_mov_b32_e32 v123, 0
	v_mov_b32_e32 v124, 0
	v_mov_b32_e32 v125, 0
	v_mov_b32_e32 v126, 0
	v_mov_b32_e32 v127, 0
	s_mov_b32 s8, 0
	s_waitcnt vmcnt(4)
	s_barrier
	s_nop 0
.Lg16_down_k:
	s_add_i32 s9, s8, 2
	s_lshl_b32 s96, s9, 13
	s_add_i32 m0, vcc_lo, 16384
	v_lshl_add_u64 v[160:161], v[188:189], 0, s[96:97]
	global_load_lds_dwordx4 v[160:161], off
	global_load_lds_dwordx4 v[160:161], off offset:1024
	ds_read_b128 v[196:199], v246 offset:0
	ds_read_b128 v[200:203], v162 offset:0
	ds_read_b128 v[204:207], v246 offset:2048
	ds_read_b128 v[242:245], v162 offset:2048
	s_add_i32 s9, s8, 2
	s_lshl_b32 s96, s9, 11
	v_lshl_add_u64 v[248:249], v[184:185], 0, s[96:97]
	v_lshl_add_u64 v[250:251], v[186:187], 0, s[96:97]
	s_waitcnt vmcnt(8) lgkmcnt(3)
	v_mfma_f32_16x16x32_bf16 v[112:115], v[196:199], v[128:131], v[112:115]
	v_mfma_f32_16x16x32_bf16 v[120:123], v[196:199], v[132:135], v[120:123]
	v_mfma_f32_16x16x32_bf16 v[48:51], v[196:199], v[136:139], v[48:51]
	v_mfma_f32_16x16x32_bf16 v[56:59], v[196:199], v[140:143], v[56:59]
	ds_read_b128 v[196:199], v246 offset:4096
	s_waitcnt lgkmcnt(3)
	v_mfma_f32_16x16x32_bf16 v[116:119], v[200:203], v[128:131], v[116:119]
	v_mfma_f32_16x16x32_bf16 v[124:127], v[200:203], v[132:135], v[124:127]
	v_mfma_f32_16x16x32_bf16 v[52:55], v[200:203], v[136:139], v[52:55]
	v_mfma_f32_16x16x32_bf16 v[60:63], v[200:203], v[140:143], v[60:63]
	ds_read_b128 v[200:203], v162 offset:4096
	s_waitcnt lgkmcnt(3)
	v_mfma_f32_16x16x32_bf16 v[96:99], v[204:207], v[128:131], v[96:99]
	v_mfma_f32_16x16x32_bf16 v[104:107], v[204:207], v[132:135], v[104:107]
	v_mfma_f32_16x16x32_bf16 v[32:35], v[204:207], v[136:139], v[32:35]
	v_mfma_f32_16x16x32_bf16 v[40:43], v[204:207], v[140:143], v[40:43]
	ds_read_b128 v[204:207], v246 offset:6144
	s_waitcnt lgkmcnt(3)
	v_mfma_f32_16x16x32_bf16 v[100:103], v[242:245], v[128:131], v[100:103]
	v_mfma_f32_16x16x32_bf16 v[108:111], v[242:245], v[132:135], v[108:111]
	v_mfma_f32_16x16x32_bf16 v[36:39], v[242:245], v[136:139], v[36:39]
	v_mfma_f32_16x16x32_bf16 v[44:47], v[242:245], v[140:143], v[44:47]
	ds_read_b128 v[242:245], v162 offset:6144
	s_waitcnt lgkmcnt(3)
	v_mfma_f32_16x16x32_bf16 v[80:83], v[196:199], v[128:131], v[80:83]
	v_mfma_f32_16x16x32_bf16 v[88:91], v[196:199], v[132:135], v[88:91]
	v_mfma_f32_16x16x32_bf16 v[16:19], v[196:199], v[136:139], v[16:19]
	v_mfma_f32_16x16x32_bf16 v[24:27], v[196:199], v[140:143], v[24:27]
	s_waitcnt lgkmcnt(2)
	v_mfma_f32_16x16x32_bf16 v[84:87], v[200:203], v[128:131], v[84:87]
	v_mfma_f32_16x16x32_bf16 v[92:95], v[200:203], v[132:135], v[92:95]
	v_mfma_f32_16x16x32_bf16 v[20:23], v[200:203], v[136:139], v[20:23]
	v_mfma_f32_16x16x32_bf16 v[28:31], v[200:203], v[140:143], v[28:31]
	s_waitcnt lgkmcnt(1)
	v_mfma_f32_16x16x32_bf16 v[64:67], v[204:207], v[128:131], v[64:67]
	v_mfma_f32_16x16x32_bf16 v[72:75], v[204:207], v[132:135], v[72:75]
	v_mfma_f32_16x16x32_bf16 v[0:3], v[204:207], v[136:139], v[0:3]
	v_mfma_f32_16x16x32_bf16 v[8:11], v[204:207], v[140:143], v[8:11]
	s_waitcnt lgkmcnt(0)
	v_mfma_f32_16x16x32_bf16 v[68:71], v[242:245], v[128:131], v[68:71]
	v_mfma_f32_16x16x32_bf16 v[76:79], v[242:245], v[132:135], v[76:79]
	v_mfma_f32_16x16x32_bf16 v[4:7], v[242:245], v[136:139], v[4:7]
	v_mfma_f32_16x16x32_bf16 v[12:15], v[242:245], v[140:143], v[12:15]
	global_load_dwordx4 v[128:131], v[248:249], off
	global_load_dwordx4 v[132:135], v[248:249], off offset:256
	global_load_dwordx4 v[136:139], v[250:251], off
	global_load_dwordx4 v[140:143], v[250:251], off offset:256
	s_waitcnt vmcnt(10)
	s_barrier
	s_add_i32 s9, s8, 3
	s_lshl_b32 s96, s9, 13
	s_mov_b32 m0, vcc_lo
	v_lshl_add_u64 v[160:161], v[188:189], 0, s[96:97]
	global_load_lds_dwordx4 v[160:161], off
	global_load_lds_dwordx4 v[160:161], off offset:1024
	ds_read_b128 v[196:199], v246 offset:8192
	ds_read_b128 v[200:203], v162 offset:8192
	ds_read_b128 v[204:207], v246 offset:10240
	ds_read_b128 v[242:245], v162 offset:10240
	s_add_i32 s9, s8, 3
	s_lshl_b32 s96, s9, 11
	v_lshl_add_u64 v[248:249], v[184:185], 0, s[96:97]
	v_lshl_add_u64 v[250:251], v[186:187], 0, s[96:97]
	s_waitcnt vmcnt(8) lgkmcnt(3)
	v_mfma_f32_16x16x32_bf16 v[112:115], v[196:199], v[144:147], v[112:115]
	v_mfma_f32_16x16x32_bf16 v[120:123], v[196:199], v[148:151], v[120:123]
	v_mfma_f32_16x16x32_bf16 v[48:51], v[196:199], v[152:155], v[48:51]
	v_mfma_f32_16x16x32_bf16 v[56:59], v[196:199], v[156:159], v[56:59]
	ds_read_b128 v[196:199], v246 offset:12288
	s_waitcnt lgkmcnt(3)
	v_mfma_f32_16x16x32_bf16 v[116:119], v[200:203], v[144:147], v[116:119]
	v_mfma_f32_16x16x32_bf16 v[124:127], v[200:203], v[148:151], v[124:127]
	v_mfma_f32_16x16x32_bf16 v[52:55], v[200:203], v[152:155], v[52:55]
	v_mfma_f32_16x16x32_bf16 v[60:63], v[200:203], v[156:159], v[60:63]
	ds_read_b128 v[200:203], v162 offset:12288
	s_waitcnt lgkmcnt(3)
	v_mfma_f32_16x16x32_bf16 v[96:99], v[204:207], v[144:147], v[96:99]
	v_mfma_f32_16x16x32_bf16 v[104:107], v[204:207], v[148:151], v[104:107]
	v_mfma_f32_16x16x32_bf16 v[32:35], v[204:207], v[152:155], v[32:35]
	v_mfma_f32_16x16x32_bf16 v[40:43], v[204:207], v[156:159], v[40:43]
	ds_read_b128 v[204:207], v246 offset:14336
	s_waitcnt lgkmcnt(3)
	v_mfma_f32_16x16x32_bf16 v[100:103], v[242:245], v[144:147], v[100:103]
	v_mfma_f32_16x16x32_bf16 v[108:111], v[242:245], v[148:151], v[108:111]
	v_mfma_f32_16x16x32_bf16 v[36:39], v[242:245], v[152:155], v[36:39]
	v_mfma_f32_16x16x32_bf16 v[44:47], v[242:245], v[156:159], v[44:47]
	ds_read_b128 v[242:245], v162 offset:14336
	s_waitcnt lgkmcnt(3)
	v_mfma_f32_16x16x32_bf16 v[80:83], v[196:199], v[144:147], v[80:83]
	v_mfma_f32_16x16x32_bf16 v[88:91], v[196:199], v[148:151], v[88:91]
	v_mfma_f32_16x16x32_bf16 v[16:19], v[196:199], v[152:155], v[16:19]
	v_mfma_f32_16x16x32_bf16 v[24:27], v[196:199], v[156:159], v[24:27]
	s_waitcnt lgkmcnt(2)
	v_mfma_f32_16x16x32_bf16 v[84:87], v[200:203], v[144:147], v[84:87]
	v_mfma_f32_16x16x32_bf16 v[92:95], v[200:203], v[148:151], v[92:95]
	v_mfma_f32_16x16x32_bf16 v[20:23], v[200:203], v[152:155], v[20:23]
	v_mfma_f32_16x16x32_bf16 v[28:31], v[200:203], v[156:159], v[28:31]
	s_waitcnt lgkmcnt(1)
	v_mfma_f32_16x16x32_bf16 v[64:67], v[204:207], v[144:147], v[64:67]
	v_mfma_f32_16x16x32_bf16 v[72:75], v[204:207], v[148:151], v[72:75]
	v_mfma_f32_16x16x32_bf16 v[0:3], v[204:207], v[152:155], v[0:3]
	v_mfma_f32_16x16x32_bf16 v[8:11], v[204:207], v[156:159], v[8:11]
	s_waitcnt lgkmcnt(0)
	v_mfma_f32_16x16x32_bf16 v[68:71], v[242:245], v[144:147], v[68:71]
	v_mfma_f32_16x16x32_bf16 v[76:79], v[242:245], v[148:151], v[76:79]
	v_mfma_f32_16x16x32_bf16 v[4:7], v[242:245], v[152:155], v[4:7]
	v_mfma_f32_16x16x32_bf16 v[12:15], v[242:245], v[156:159], v[12:15]
	global_load_dwordx4 v[144:147], v[248:249], off
	global_load_dwordx4 v[148:151], v[248:249], off offset:256
	global_load_dwordx4 v[152:155], v[250:251], off
	global_load_dwordx4 v[156:159], v[250:251], off offset:256
	s_waitcnt vmcnt(10)
	s_barrier
	s_add_i32 s9, s8, 4
	s_lshl_b32 s96, s9, 13
	s_add_i32 m0, vcc_lo, 8192
	v_lshl_add_u64 v[160:161], v[188:189], 0, s[96:97]
	global_load_lds_dwordx4 v[160:161], off
	global_load_lds_dwordx4 v[160:161], off offset:1024
	ds_read_b128 v[196:199], v246 offset:16384
	ds_read_b128 v[200:203], v162 offset:16384
	ds_read_b128 v[204:207], v246 offset:18432
	ds_read_b128 v[242:245], v162 offset:18432
	s_add_i32 s9, s8, 4
	s_lshl_b32 s96, s9, 11
	v_lshl_add_u64 v[248:249], v[184:185], 0, s[96:97]
	v_lshl_add_u64 v[250:251], v[186:187], 0, s[96:97]
	s_waitcnt vmcnt(8) lgkmcnt(3)
	v_mfma_f32_16x16x32_bf16 v[112:115], v[196:199], v[128:131], v[112:115]
	v_mfma_f32_16x16x32_bf16 v[120:123], v[196:199], v[132:135], v[120:123]
	v_mfma_f32_16x16x32_bf16 v[48:51], v[196:199], v[136:139], v[48:51]
	v_mfma_f32_16x16x32_bf16 v[56:59], v[196:199], v[140:143], v[56:59]
	ds_read_b128 v[196:199], v246 offset:20480
	s_waitcnt lgkmcnt(3)
	v_mfma_f32_16x16x32_bf16 v[116:119], v[200:203], v[128:131], v[116:119]
	v_mfma_f32_16x16x32_bf16 v[124:127], v[200:203], v[132:135], v[124:127]
	v_mfma_f32_16x16x32_bf16 v[52:55], v[200:203], v[136:139], v[52:55]
	v_mfma_f32_16x16x32_bf16 v[60:63], v[200:203], v[140:143], v[60:63]
	ds_read_b128 v[200:203], v162 offset:20480
	s_waitcnt lgkmcnt(3)
	v_mfma_f32_16x16x32_bf16 v[96:99], v[204:207], v[128:131], v[96:99]
	v_mfma_f32_16x16x32_bf16 v[104:107], v[204:207], v[132:135], v[104:107]
	v_mfma_f32_16x16x32_bf16 v[32:35], v[204:207], v[136:139], v[32:35]
	v_mfma_f32_16x16x32_bf16 v[40:43], v[204:207], v[140:143], v[40:43]
	ds_read_b128 v[204:207], v246 offset:22528
	s_waitcnt lgkmcnt(3)
	v_mfma_f32_16x16x32_bf16 v[100:103], v[242:245], v[128:131], v[100:103]
	v_mfma_f32_16x16x32_bf16 v[108:111], v[242:245], v[132:135], v[108:111]
	v_mfma_f32_16x16x32_bf16 v[36:39], v[242:245], v[136:139], v[36:39]
	v_mfma_f32_16x16x32_bf16 v[44:47], v[242:245], v[140:143], v[44:47]
	ds_read_b128 v[242:245], v162 offset:22528
	s_waitcnt lgkmcnt(3)
	v_mfma_f32_16x16x32_bf16 v[80:83], v[196:199], v[128:131], v[80:83]
	v_mfma_f32_16x16x32_bf16 v[88:91], v[196:199], v[132:135], v[88:91]
	v_mfma_f32_16x16x32_bf16 v[16:19], v[196:199], v[136:139], v[16:19]
	v_mfma_f32_16x16x32_bf16 v[24:27], v[196:199], v[140:143], v[24:27]
	s_waitcnt lgkmcnt(2)
	v_mfma_f32_16x16x32_bf16 v[84:87], v[200:203], v[128:131], v[84:87]
	v_mfma_f32_16x16x32_bf16 v[92:95], v[200:203], v[132:135], v[92:95]
	v_mfma_f32_16x16x32_bf16 v[20:23], v[200:203], v[136:139], v[20:23]
	v_mfma_f32_16x16x32_bf16 v[28:31], v[200:203], v[140:143], v[28:31]
	s_waitcnt lgkmcnt(1)
	v_mfma_f32_16x16x32_bf16 v[64:67], v[204:207], v[128:131], v[64:67]
	v_mfma_f32_16x16x32_bf16 v[72:75], v[204:207], v[132:135], v[72:75]
	v_mfma_f32_16x16x32_bf16 v[0:3], v[204:207], v[136:139], v[0:3]
	v_mfma_f32_16x16x32_bf16 v[8:11], v[204:207], v[140:143], v[8:11]
	s_waitcnt lgkmcnt(0)
	v_mfma_f32_16x16x32_bf16 v[68:71], v[242:245], v[128:131], v[68:71]
	v_mfma_f32_16x16x32_bf16 v[76:79], v[242:245], v[132:135], v[76:79]
	v_mfma_f32_16x16x32_bf16 v[4:7], v[242:245], v[136:139], v[4:7]
	v_mfma_f32_16x16x32_bf16 v[12:15], v[242:245], v[140:143], v[12:15]
	global_load_dwordx4 v[128:131], v[248:249], off
	global_load_dwordx4 v[132:135], v[248:249], off offset:256
	global_load_dwordx4 v[136:139], v[250:251], off
	global_load_dwordx4 v[140:143], v[250:251], off offset:256
	s_waitcnt vmcnt(10)
	s_barrier
	s_add_i32 s9, s8, 5
	s_lshl_b32 s96, s9, 13
	s_add_i32 m0, vcc_lo, 16384
	v_lshl_add_u64 v[160:161], v[188:189], 0, s[96:97]
	global_load_lds_dwordx4 v[160:161], off
	global_load_lds_dwordx4 v[160:161], off offset:1024
	ds_read_b128 v[196:199], v246 offset:0
	ds_read_b128 v[200:203], v162 offset:0
	ds_read_b128 v[204:207], v246 offset:2048
	ds_read_b128 v[242:245], v162 offset:2048
	s_add_i32 s9, s8, 5
	s_lshl_b32 s96, s9, 11
	v_lshl_add_u64 v[248:249], v[184:185], 0, s[96:97]
	v_lshl_add_u64 v[250:251], v[186:187], 0, s[96:97]
	s_waitcnt vmcnt(8) lgkmcnt(3)
	v_mfma_f32_16x16x32_bf16 v[112:115], v[196:199], v[144:147], v[112:115]
	v_mfma_f32_16x16x32_bf16 v[120:123], v[196:199], v[148:151], v[120:123]
	v_mfma_f32_16x16x32_bf16 v[48:51], v[196:199], v[152:155], v[48:51]
	v_mfma_f32_16x16x32_bf16 v[56:59], v[196:199], v[156:159], v[56:59]
	ds_read_b128 v[196:199], v246 offset:4096
	s_waitcnt lgkmcnt(3)
	v_mfma_f32_16x16x32_bf16 v[116:119], v[200:203], v[144:147], v[116:119]
	v_mfma_f32_16x16x32_bf16 v[124:127], v[200:203], v[148:151], v[124:127]
	v_mfma_f32_16x16x32_bf16 v[52:55], v[200:203], v[152:155], v[52:55]
	v_mfma_f32_16x16x32_bf16 v[60:63], v[200:203], v[156:159], v[60:63]
	ds_read_b128 v[200:203], v162 offset:4096
	s_waitcnt lgkmcnt(3)
	v_mfma_f32_16x16x32_bf16 v[96:99], v[204:207], v[144:147], v[96:99]
	v_mfma_f32_16x16x32_bf16 v[104:107], v[204:207], v[148:151], v[104:107]
	v_mfma_f32_16x16x32_bf16 v[32:35], v[204:207], v[152:155], v[32:35]
	v_mfma_f32_16x16x32_bf16 v[40:43], v[204:207], v[156:159], v[40:43]
	ds_read_b128 v[204:207], v246 offset:6144
	s_waitcnt lgkmcnt(3)
	v_mfma_f32_16x16x32_bf16 v[100:103], v[242:245], v[144:147], v[100:103]
	v_mfma_f32_16x16x32_bf16 v[108:111], v[242:245], v[148:151], v[108:111]
	v_mfma_f32_16x16x32_bf16 v[36:39], v[242:245], v[152:155], v[36:39]
	v_mfma_f32_16x16x32_bf16 v[44:47], v[242:245], v[156:159], v[44:47]
	ds_read_b128 v[242:245], v162 offset:6144
	s_waitcnt lgkmcnt(3)
	v_mfma_f32_16x16x32_bf16 v[80:83], v[196:199], v[144:147], v[80:83]
	v_mfma_f32_16x16x32_bf16 v[88:91], v[196:199], v[148:151], v[88:91]
	v_mfma_f32_16x16x32_bf16 v[16:19], v[196:199], v[152:155], v[16:19]
	v_mfma_f32_16x16x32_bf16 v[24:27], v[196:199], v[156:159], v[24:27]
	s_waitcnt lgkmcnt(2)
	v_mfma_f32_16x16x32_bf16 v[84:87], v[200:203], v[144:147], v[84:87]
	v_mfma_f32_16x16x32_bf16 v[92:95], v[200:203], v[148:151], v[92:95]
	v_mfma_f32_16x16x32_bf16 v[20:23], v[200:203], v[152:155], v[20:23]
	v_mfma_f32_16x16x32_bf16 v[28:31], v[200:203], v[156:159], v[28:31]
	s_waitcnt lgkmcnt(1)
	v_mfma_f32_16x16x32_bf16 v[64:67], v[204:207], v[144:147], v[64:67]
	v_mfma_f32_16x16x32_bf16 v[72:75], v[204:207], v[148:151], v[72:75]
	v_mfma_f32_16x16x32_bf16 v[0:3], v[204:207], v[152:155], v[0:3]
	v_mfma_f32_16x16x32_bf16 v[8:11], v[204:207], v[156:159], v[8:11]
	s_waitcnt lgkmcnt(0)
	v_mfma_f32_16x16x32_bf16 v[68:71], v[242:245], v[144:147], v[68:71]
	v_mfma_f32_16x16x32_bf16 v[76:79], v[242:245], v[148:151], v[76:79]
	v_mfma_f32_16x16x32_bf16 v[4:7], v[242:245], v[152:155], v[4:7]
	v_mfma_f32_16x16x32_bf16 v[12:15], v[242:245], v[156:159], v[12:15]
	global_load_dwordx4 v[144:147], v[248:249], off
	global_load_dwordx4 v[148:151], v[248:249], off offset:256
	global_load_dwordx4 v[152:155], v[250:251], off
	global_load_dwordx4 v[156:159], v[250:251], off offset:256
	s_waitcnt vmcnt(10)
	s_barrier
	s_add_i32 s9, s8, 6
	s_lshl_b32 s96, s9, 13
	s_mov_b32 m0, vcc_lo
	v_lshl_add_u64 v[160:161], v[188:189], 0, s[96:97]
	global_load_lds_dwordx4 v[160:161], off
	global_load_lds_dwordx4 v[160:161], off offset:1024
	ds_read_b128 v[196:199], v246 offset:8192
	ds_read_b128 v[200:203], v162 offset:8192
	ds_read_b128 v[204:207], v246 offset:10240
	ds_read_b128 v[242:245], v162 offset:10240
	s_add_i32 s9, s8, 6
	s_lshl_b32 s96, s9, 11
	v_lshl_add_u64 v[248:249], v[184:185], 0, s[96:97]
	v_lshl_add_u64 v[250:251], v[186:187], 0, s[96:97]
	s_waitcnt vmcnt(8) lgkmcnt(3)
	v_mfma_f32_16x16x32_bf16 v[112:115], v[196:199], v[128:131], v[112:115]
	v_mfma_f32_16x16x32_bf16 v[120:123], v[196:199], v[132:135], v[120:123]
	v_mfma_f32_16x16x32_bf16 v[48:51], v[196:199], v[136:139], v[48:51]
	v_mfma_f32_16x16x32_bf16 v[56:59], v[196:199], v[140:143], v[56:59]
	ds_read_b128 v[196:199], v246 offset:12288
	s_waitcnt lgkmcnt(3)
	v_mfma_f32_16x16x32_bf16 v[116:119], v[200:203], v[128:131], v[116:119]
	v_mfma_f32_16x16x32_bf16 v[124:127], v[200:203], v[132:135], v[124:127]
	v_mfma_f32_16x16x32_bf16 v[52:55], v[200:203], v[136:139], v[52:55]
	v_mfma_f32_16x16x32_bf16 v[60:63], v[200:203], v[140:143], v[60:63]
	ds_read_b128 v[200:203], v162 offset:12288
	s_waitcnt lgkmcnt(3)
	v_mfma_f32_16x16x32_bf16 v[96:99], v[204:207], v[128:131], v[96:99]
	v_mfma_f32_16x16x32_bf16 v[104:107], v[204:207], v[132:135], v[104:107]
	v_mfma_f32_16x16x32_bf16 v[32:35], v[204:207], v[136:139], v[32:35]
	v_mfma_f32_16x16x32_bf16 v[40:43], v[204:207], v[140:143], v[40:43]
	ds_read_b128 v[204:207], v246 offset:14336
	s_waitcnt lgkmcnt(3)
	v_mfma_f32_16x16x32_bf16 v[100:103], v[242:245], v[128:131], v[100:103]
	v_mfma_f32_16x16x32_bf16 v[108:111], v[242:245], v[132:135], v[108:111]
	v_mfma_f32_16x16x32_bf16 v[36:39], v[242:245], v[136:139], v[36:39]
	v_mfma_f32_16x16x32_bf16 v[44:47], v[242:245], v[140:143], v[44:47]
	ds_read_b128 v[242:245], v162 offset:14336
	s_waitcnt lgkmcnt(3)
	v_mfma_f32_16x16x32_bf16 v[80:83], v[196:199], v[128:131], v[80:83]
	v_mfma_f32_16x16x32_bf16 v[88:91], v[196:199], v[132:135], v[88:91]
	v_mfma_f32_16x16x32_bf16 v[16:19], v[196:199], v[136:139], v[16:19]
	v_mfma_f32_16x16x32_bf16 v[24:27], v[196:199], v[140:143], v[24:27]
	s_waitcnt lgkmcnt(2)
	v_mfma_f32_16x16x32_bf16 v[84:87], v[200:203], v[128:131], v[84:87]
	v_mfma_f32_16x16x32_bf16 v[92:95], v[200:203], v[132:135], v[92:95]
	v_mfma_f32_16x16x32_bf16 v[20:23], v[200:203], v[136:139], v[20:23]
	v_mfma_f32_16x16x32_bf16 v[28:31], v[200:203], v[140:143], v[28:31]
	s_waitcnt lgkmcnt(1)
	v_mfma_f32_16x16x32_bf16 v[64:67], v[204:207], v[128:131], v[64:67]
	v_mfma_f32_16x16x32_bf16 v[72:75], v[204:207], v[132:135], v[72:75]
	v_mfma_f32_16x16x32_bf16 v[0:3], v[204:207], v[136:139], v[0:3]
	v_mfma_f32_16x16x32_bf16 v[8:11], v[204:207], v[140:143], v[8:11]
	s_waitcnt lgkmcnt(0)
	v_mfma_f32_16x16x32_bf16 v[68:71], v[242:245], v[128:131], v[68:71]
	v_mfma_f32_16x16x32_bf16 v[76:79], v[242:245], v[132:135], v[76:79]
	v_mfma_f32_16x16x32_bf16 v[4:7], v[242:245], v[136:139], v[4:7]
	v_mfma_f32_16x16x32_bf16 v[12:15], v[242:245], v[140:143], v[12:15]
	global_load_dwordx4 v[128:131], v[248:249], off
	global_load_dwordx4 v[132:135], v[248:249], off offset:256
	global_load_dwordx4 v[136:139], v[250:251], off
	global_load_dwordx4 v[140:143], v[250:251], off offset:256
	s_waitcnt vmcnt(10)
	s_barrier
	s_add_i32 s9, s8, 7
	s_lshl_b32 s96, s9, 13
	s_add_i32 m0, vcc_lo, 8192
	v_lshl_add_u64 v[160:161], v[188:189], 0, s[96:97]
	global_load_lds_dwordx4 v[160:161], off
	global_load_lds_dwordx4 v[160:161], off offset:1024
	ds_read_b128 v[196:199], v246 offset:16384
	ds_read_b128 v[200:203], v162 offset:16384
	ds_read_b128 v[204:207], v246 offset:18432
	ds_read_b128 v[242:245], v162 offset:18432
	s_add_i32 s9, s8, 7
	s_lshl_b32 s96, s9, 11
	v_lshl_add_u64 v[248:249], v[184:185], 0, s[96:97]
	v_lshl_add_u64 v[250:251], v[186:187], 0, s[96:97]
	s_waitcnt vmcnt(8) lgkmcnt(3)
	v_mfma_f32_16x16x32_bf16 v[112:115], v[196:199], v[144:147], v[112:115]
	v_mfma_f32_16x16x32_bf16 v[120:123], v[196:199], v[148:151], v[120:123]
	v_mfma_f32_16x16x32_bf16 v[48:51], v[196:199], v[152:155], v[48:51]
	v_mfma_f32_16x16x32_bf16 v[56:59], v[196:199], v[156:159], v[56:59]
	ds_read_b128 v[196:199], v246 offset:20480
	s_waitcnt lgkmcnt(3)
	v_mfma_f32_16x16x32_bf16 v[116:119], v[200:203], v[144:147], v[116:119]
	v_mfma_f32_16x16x32_bf16 v[124:127], v[200:203], v[148:151], v[124:127]
	v_mfma_f32_16x16x32_bf16 v[52:55], v[200:203], v[152:155], v[52:55]
	v_mfma_f32_16x16x32_bf16 v[60:63], v[200:203], v[156:159], v[60:63]
	ds_read_b128 v[200:203], v162 offset:20480
	s_waitcnt lgkmcnt(3)
	v_mfma_f32_16x16x32_bf16 v[96:99], v[204:207], v[144:147], v[96:99]
	v_mfma_f32_16x16x32_bf16 v[104:107], v[204:207], v[148:151], v[104:107]
	v_mfma_f32_16x16x32_bf16 v[32:35], v[204:207], v[152:155], v[32:35]
	v_mfma_f32_16x16x32_bf16 v[40:43], v[204:207], v[156:159], v[40:43]
	ds_read_b128 v[204:207], v246 offset:22528
	s_waitcnt lgkmcnt(3)
	v_mfma_f32_16x16x32_bf16 v[100:103], v[242:245], v[144:147], v[100:103]
	v_mfma_f32_16x16x32_bf16 v[108:111], v[242:245], v[148:151], v[108:111]
	v_mfma_f32_16x16x32_bf16 v[36:39], v[242:245], v[152:155], v[36:39]
	v_mfma_f32_16x16x32_bf16 v[44:47], v[242:245], v[156:159], v[44:47]
	ds_read_b128 v[242:245], v162 offset:22528
	s_waitcnt lgkmcnt(3)
	v_mfma_f32_16x16x32_bf16 v[80:83], v[196:199], v[144:147], v[80:83]
	v_mfma_f32_16x16x32_bf16 v[88:91], v[196:199], v[148:151], v[88:91]
	v_mfma_f32_16x16x32_bf16 v[16:19], v[196:199], v[152:155], v[16:19]
	v_mfma_f32_16x16x32_bf16 v[24:27], v[196:199], v[156:159], v[24:27]
	s_waitcnt lgkmcnt(2)
	v_mfma_f32_16x16x32_bf16 v[84:87], v[200:203], v[144:147], v[84:87]
	v_mfma_f32_16x16x32_bf16 v[92:95], v[200:203], v[148:151], v[92:95]
	v_mfma_f32_16x16x32_bf16 v[20:23], v[200:203], v[152:155], v[20:23]
	v_mfma_f32_16x16x32_bf16 v[28:31], v[200:203], v[156:159], v[28:31]
	s_waitcnt lgkmcnt(1)
	v_mfma_f32_16x16x32_bf16 v[64:67], v[204:207], v[144:147], v[64:67]
	v_mfma_f32_16x16x32_bf16 v[72:75], v[204:207], v[148:151], v[72:75]
	v_mfma_f32_16x16x32_bf16 v[0:3], v[204:207], v[152:155], v[0:3]
	v_mfma_f32_16x16x32_bf16 v[8:11], v[204:207], v[156:159], v[8:11]
	s_waitcnt lgkmcnt(0)
	v_mfma_f32_16x16x32_bf16 v[68:71], v[242:245], v[144:147], v[68:71]
	v_mfma_f32_16x16x32_bf16 v[76:79], v[242:245], v[148:151], v[76:79]
	v_mfma_f32_16x16x32_bf16 v[4:7], v[242:245], v[152:155], v[4:7]
	v_mfma_f32_16x16x32_bf16 v[12:15], v[242:245], v[156:159], v[12:15]
	global_load_dwordx4 v[144:147], v[248:249], off
	global_load_dwordx4 v[148:151], v[248:249], off offset:256
	global_load_dwordx4 v[152:155], v[250:251], off
	global_load_dwordx4 v[156:159], v[250:251], off offset:256
	s_waitcnt vmcnt(10)
	s_barrier
	s_add_i32 s8, s8, 6
	s_cmp_lt_u32 s8, 84
	s_cbranch_scc1 .Lg16_down_k
	s_mov_b32 s96, 0xac000
	s_add_i32 m0, vcc_lo, 16384
	v_lshl_add_u64 v[160:161], v[188:189], 0, s[96:97]
	global_load_lds_dwordx4 v[160:161], off
	global_load_lds_dwordx4 v[160:161], off offset:1024
	ds_read_b128 v[196:199], v246 offset:0
	ds_read_b128 v[200:203], v162 offset:0
	ds_read_b128 v[204:207], v246 offset:2048
	ds_read_b128 v[242:245], v162 offset:2048
	s_mov_b32 s96, 0x2b000
	v_lshl_add_u64 v[248:249], v[184:185], 0, s[96:97]
	v_lshl_add_u64 v[250:251], v[186:187], 0, s[96:97]
	s_waitcnt vmcnt(8) lgkmcnt(3)
	v_mfma_f32_16x16x32_bf16 v[112:115], v[196:199], v[128:131], v[112:115]
	v_mfma_f32_16x16x32_bf16 v[120:123], v[196:199], v[132:135], v[120:123]
	v_mfma_f32_16x16x32_bf16 v[48:51], v[196:199], v[136:139], v[48:51]
	v_mfma_f32_16x16x32_bf16 v[56:59], v[196:199], v[140:143], v[56:59]
	ds_read_b128 v[196:199], v246 offset:4096
	s_waitcnt lgkmcnt(3)
	v_mfma_f32_16x16x32_bf16 v[116:119], v[200:203], v[128:131], v[116:119]
	v_mfma_f32_16x16x32_bf16 v[124:127], v[200:203], v[132:135], v[124:127]
	v_mfma_f32_16x16x32_bf16 v[52:55], v[200:203], v[136:139], v[52:55]
	v_mfma_f32_16x16x32_bf16 v[60:63], v[200:203], v[140:143], v[60:63]
	ds_read_b128 v[200:203], v162 offset:4096
	s_waitcnt lgkmcnt(3)
	v_mfma_f32_16x16x32_bf16 v[96:99], v[204:207], v[128:131], v[96:99]
	v_mfma_f32_16x16x32_bf16 v[104:107], v[204:207], v[132:135], v[104:107]
	v_mfma_f32_16x16x32_bf16 v[32:35], v[204:207], v[136:139], v[32:35]
	v_mfma_f32_16x16x32_bf16 v[40:43], v[204:207], v[140:143], v[40:43]
	ds_read_b128 v[204:207], v246 offset:6144
	s_waitcnt lgkmcnt(3)
	v_mfma_f32_16x16x32_bf16 v[100:103], v[242:245], v[128:131], v[100:103]
	v_mfma_f32_16x16x32_bf16 v[108:111], v[242:245], v[132:135], v[108:111]
	v_mfma_f32_16x16x32_bf16 v[36:39], v[242:245], v[136:139], v[36:39]
	v_mfma_f32_16x16x32_bf16 v[44:47], v[242:245], v[140:143], v[44:47]
	ds_read_b128 v[242:245], v162 offset:6144
	s_waitcnt lgkmcnt(3)
	v_mfma_f32_16x16x32_bf16 v[80:83], v[196:199], v[128:131], v[80:83]
	v_mfma_f32_16x16x32_bf16 v[88:91], v[196:199], v[132:135], v[88:91]
	v_mfma_f32_16x16x32_bf16 v[16:19], v[196:199], v[136:139], v[16:19]
	v_mfma_f32_16x16x32_bf16 v[24:27], v[196:199], v[140:143], v[24:27]
	s_waitcnt lgkmcnt(2)
	v_mfma_f32_16x16x32_bf16 v[84:87], v[200:203], v[128:131], v[84:87]
	v_mfma_f32_16x16x32_bf16 v[92:95], v[200:203], v[132:135], v[92:95]
	v_mfma_f32_16x16x32_bf16 v[20:23], v[200:203], v[136:139], v[20:23]
	v_mfma_f32_16x16x32_bf16 v[28:31], v[200:203], v[140:143], v[28:31]
	s_waitcnt lgkmcnt(1)
	v_mfma_f32_16x16x32_bf16 v[64:67], v[204:207], v[128:131], v[64:67]
	v_mfma_f32_16x16x32_bf16 v[72:75], v[204:207], v[132:135], v[72:75]
	v_mfma_f32_16x16x32_bf16 v[0:3], v[204:207], v[136:139], v[0:3]
	v_mfma_f32_16x16x32_bf16 v[8:11], v[204:207], v[140:143], v[8:11]
	s_waitcnt lgkmcnt(0)
	v_mfma_f32_16x16x32_bf16 v[68:71], v[242:245], v[128:131], v[68:71]
	v_mfma_f32_16x16x32_bf16 v[76:79], v[242:245], v[132:135], v[76:79]
	v_mfma_f32_16x16x32_bf16 v[4:7], v[242:245], v[136:139], v[4:7]
	v_mfma_f32_16x16x32_bf16 v[12:15], v[242:245], v[140:143], v[12:15]
	global_load_dwordx4 v[128:131], v[248:249], off
	global_load_dwordx4 v[132:135], v[248:249], off offset:256
	global_load_dwordx4 v[136:139], v[250:251], off
	global_load_dwordx4 v[140:143], v[250:251], off offset:256
	s_waitcnt vmcnt(10)
	s_barrier
	s_mov_b32 s96, 0xae000
	s_mov_b32 m0, vcc_lo
	v_lshl_add_u64 v[160:161], v[188:189], 0, s[96:97]
	global_load_lds_dwordx4 v[160:161], off
	global_load_lds_dwordx4 v[160:161], off offset:1024
	ds_read_b128 v[196:199], v246 offset:8192
	ds_read_b128 v[200:203], v162 offset:8192
	ds_read_b128 v[204:207], v246 offset:10240
	ds_read_b128 v[242:245], v162 offset:10240
	s_mov_b32 s96, 0x2b800
	v_lshl_add_u64 v[248:249], v[184:185], 0, s[96:97]
	v_lshl_add_u64 v[250:251], v[186:187], 0, s[96:97]
	s_waitcnt vmcnt(8) lgkmcnt(3)
	v_mfma_f32_16x16x32_bf16 v[112:115], v[196:199], v[144:147], v[112:115]
	v_mfma_f32_16x16x32_bf16 v[120:123], v[196:199], v[148:151], v[120:123]
	v_mfma_f32_16x16x32_bf16 v[48:51], v[196:199], v[152:155], v[48:51]
	v_mfma_f32_16x16x32_bf16 v[56:59], v[196:199], v[156:159], v[56:59]
	ds_read_b128 v[196:199], v246 offset:12288
	s_waitcnt lgkmcnt(3)
	v_mfma_f32_16x16x32_bf16 v[116:119], v[200:203], v[144:147], v[116:119]
	v_mfma_f32_16x16x32_bf16 v[124:127], v[200:203], v[148:151], v[124:127]
	v_mfma_f32_16x16x32_bf16 v[52:55], v[200:203], v[152:155], v[52:55]
	v_mfma_f32_16x16x32_bf16 v[60:63], v[200:203], v[156:159], v[60:63]
	ds_read_b128 v[200:203], v162 offset:12288
	s_waitcnt lgkmcnt(3)
	v_mfma_f32_16x16x32_bf16 v[96:99], v[204:207], v[144:147], v[96:99]
	v_mfma_f32_16x16x32_bf16 v[104:107], v[204:207], v[148:151], v[104:107]
	v_mfma_f32_16x16x32_bf16 v[32:35], v[204:207], v[152:155], v[32:35]
	v_mfma_f32_16x16x32_bf16 v[40:43], v[204:207], v[156:159], v[40:43]
	ds_read_b128 v[204:207], v246 offset:14336
	s_waitcnt lgkmcnt(3)
	v_mfma_f32_16x16x32_bf16 v[100:103], v[242:245], v[144:147], v[100:103]
	v_mfma_f32_16x16x32_bf16 v[108:111], v[242:245], v[148:151], v[108:111]
	v_mfma_f32_16x16x32_bf16 v[36:39], v[242:245], v[152:155], v[36:39]
	v_mfma_f32_16x16x32_bf16 v[44:47], v[242:245], v[156:159], v[44:47]
	ds_read_b128 v[242:245], v162 offset:14336
	s_waitcnt lgkmcnt(3)
	v_mfma_f32_16x16x32_bf16 v[80:83], v[196:199], v[144:147], v[80:83]
	v_mfma_f32_16x16x32_bf16 v[88:91], v[196:199], v[148:151], v[88:91]
	v_mfma_f32_16x16x32_bf16 v[16:19], v[196:199], v[152:155], v[16:19]
	v_mfma_f32_16x16x32_bf16 v[24:27], v[196:199], v[156:159], v[24:27]
	s_waitcnt lgkmcnt(2)
	v_mfma_f32_16x16x32_bf16 v[84:87], v[200:203], v[144:147], v[84:87]
	v_mfma_f32_16x16x32_bf16 v[92:95], v[200:203], v[148:151], v[92:95]
	v_mfma_f32_16x16x32_bf16 v[20:23], v[200:203], v[152:155], v[20:23]
	v_mfma_f32_16x16x32_bf16 v[28:31], v[200:203], v[156:159], v[28:31]
	s_waitcnt lgkmcnt(1)
	v_mfma_f32_16x16x32_bf16 v[64:67], v[204:207], v[144:147], v[64:67]
	v_mfma_f32_16x16x32_bf16 v[72:75], v[204:207], v[148:151], v[72:75]
	v_mfma_f32_16x16x32_bf16 v[0:3], v[204:207], v[152:155], v[0:3]
	v_mfma_f32_16x16x32_bf16 v[8:11], v[204:207], v[156:159], v[8:11]
	s_waitcnt lgkmcnt(0)
	v_mfma_f32_16x16x32_bf16 v[68:71], v[242:245], v[144:147], v[68:71]
	v_mfma_f32_16x16x32_bf16 v[76:79], v[242:245], v[148:151], v[76:79]
	v_mfma_f32_16x16x32_bf16 v[4:7], v[242:245], v[152:155], v[4:7]
	v_mfma_f32_16x16x32_bf16 v[12:15], v[242:245], v[156:159], v[12:15]
	global_load_dwordx4 v[144:147], v[248:249], off
	global_load_dwordx4 v[148:151], v[248:249], off offset:256
	global_load_dwordx4 v[152:155], v[250:251], off
	global_load_dwordx4 v[156:159], v[250:251], off offset:256
	s_waitcnt vmcnt(10)
	s_barrier
	ds_read_b128 v[196:199], v246 offset:16384
	ds_read_b128 v[200:203], v162 offset:16384
	ds_read_b128 v[204:207], v246 offset:18432
	ds_read_b128 v[242:245], v162 offset:18432
	s_waitcnt vmcnt(6) lgkmcnt(3)
	v_mfma_f32_16x16x32_bf16 v[112:115], v[196:199], v[128:131], v[112:115]
	v_mfma_f32_16x16x32_bf16 v[120:123], v[196:199], v[132:135], v[120:123]
	v_mfma_f32_16x16x32_bf16 v[48:51], v[196:199], v[136:139], v[48:51]
	v_mfma_f32_16x16x32_bf16 v[56:59], v[196:199], v[140:143], v[56:59]
	ds_read_b128 v[196:199], v246 offset:20480
	s_waitcnt lgkmcnt(3)
	v_mfma_f32_16x16x32_bf16 v[116:119], v[200:203], v[128:131], v[116:119]
	v_mfma_f32_16x16x32_bf16 v[124:127], v[200:203], v[132:135], v[124:127]
	v_mfma_f32_16x16x32_bf16 v[52:55], v[200:203], v[136:139], v[52:55]
	v_mfma_f32_16x16x32_bf16 v[60:63], v[200:203], v[140:143], v[60:63]
	ds_read_b128 v[200:203], v162 offset:20480
	s_waitcnt lgkmcnt(3)
	v_mfma_f32_16x16x32_bf16 v[96:99], v[204:207], v[128:131], v[96:99]
	v_mfma_f32_16x16x32_bf16 v[104:107], v[204:207], v[132:135], v[104:107]
	v_mfma_f32_16x16x32_bf16 v[32:35], v[204:207], v[136:139], v[32:35]
	v_mfma_f32_16x16x32_bf16 v[40:43], v[204:207], v[140:143], v[40:43]
	ds_read_b128 v[204:207], v246 offset:22528
	s_waitcnt lgkmcnt(3)
	v_mfma_f32_16x16x32_bf16 v[100:103], v[242:245], v[128:131], v[100:103]
	v_mfma_f32_16x16x32_bf16 v[108:111], v[242:245], v[132:135], v[108:111]
	v_mfma_f32_16x16x32_bf16 v[36:39], v[242:245], v[136:139], v[36:39]
	v_mfma_f32_16x16x32_bf16 v[44:47], v[242:245], v[140:143], v[44:47]
	ds_read_b128 v[242:245], v162 offset:22528
	s_waitcnt lgkmcnt(3)
	v_mfma_f32_16x16x32_bf16 v[80:83], v[196:199], v[128:131], v[80:83]
	v_mfma_f32_16x16x32_bf16 v[88:91], v[196:199], v[132:135], v[88:91]
	v_mfma_f32_16x16x32_bf16 v[16:19], v[196:199], v[136:139], v[16:19]
	v_mfma_f32_16x16x32_bf16 v[24:27], v[196:199], v[140:143], v[24:27]
	s_waitcnt lgkmcnt(2)
	v_mfma_f32_16x16x32_bf16 v[84:87], v[200:203], v[128:131], v[84:87]
	v_mfma_f32_16x16x32_bf16 v[92:95], v[200:203], v[132:135], v[92:95]
	v_mfma_f32_16x16x32_bf16 v[20:23], v[200:203], v[136:139], v[20:23]
	v_mfma_f32_16x16x32_bf16 v[28:31], v[200:203], v[140:143], v[28:31]
	s_waitcnt lgkmcnt(1)
	v_mfma_f32_16x16x32_bf16 v[64:67], v[204:207], v[128:131], v[64:67]
	v_mfma_f32_16x16x32_bf16 v[72:75], v[204:207], v[132:135], v[72:75]
	v_mfma_f32_16x16x32_bf16 v[0:3], v[204:207], v[136:139], v[0:3]
	v_mfma_f32_16x16x32_bf16 v[8:11], v[204:207], v[140:143], v[8:11]
	s_waitcnt lgkmcnt(0)
	v_mfma_f32_16x16x32_bf16 v[68:71], v[242:245], v[128:131], v[68:71]
	v_mfma_f32_16x16x32_bf16 v[76:79], v[242:245], v[132:135], v[76:79]
	v_mfma_f32_16x16x32_bf16 v[4:7], v[242:245], v[136:139], v[4:7]
	v_mfma_f32_16x16x32_bf16 v[12:15], v[242:245], v[140:143], v[12:15]
	s_waitcnt vmcnt(4)
	s_barrier
	ds_read_b128 v[196:199], v246 offset:0
	ds_read_b128 v[200:203], v162 offset:0
	ds_read_b128 v[204:207], v246 offset:2048
	ds_read_b128 v[242:245], v162 offset:2048
	s_waitcnt vmcnt(0) lgkmcnt(3)
	v_mfma_f32_16x16x32_bf16 v[112:115], v[196:199], v[144:147], v[112:115]
	v_mfma_f32_16x16x32_bf16 v[120:123], v[196:199], v[148:151], v[120:123]
	v_mfma_f32_16x16x32_bf16 v[48:51], v[196:199], v[152:155], v[48:51]
	v_mfma_f32_16x16x32_bf16 v[56:59], v[196:199], v[156:159], v[56:59]
	ds_read_b128 v[196:199], v246 offset:4096
	s_waitcnt lgkmcnt(3)
	v_mfma_f32_16x16x32_bf16 v[116:119], v[200:203], v[144:147], v[116:119]
	v_mfma_f32_16x16x32_bf16 v[124:127], v[200:203], v[148:151], v[124:127]
	v_mfma_f32_16x16x32_bf16 v[52:55], v[200:203], v[152:155], v[52:55]
	v_mfma_f32_16x16x32_bf16 v[60:63], v[200:203], v[156:159], v[60:63]
	ds_read_b128 v[200:203], v162 offset:4096
	s_waitcnt lgkmcnt(3)
	v_mfma_f32_16x16x32_bf16 v[96:99], v[204:207], v[144:147], v[96:99]
	v_mfma_f32_16x16x32_bf16 v[104:107], v[204:207], v[148:151], v[104:107]
	v_mfma_f32_16x16x32_bf16 v[32:35], v[204:207], v[152:155], v[32:35]
	v_mfma_f32_16x16x32_bf16 v[40:43], v[204:207], v[156:159], v[40:43]
	ds_read_b128 v[204:207], v246 offset:6144
	s_waitcnt lgkmcnt(3)
	v_mfma_f32_16x16x32_bf16 v[100:103], v[242:245], v[144:147], v[100:103]
	v_mfma_f32_16x16x32_bf16 v[108:111], v[242:245], v[148:151], v[108:111]
	v_mfma_f32_16x16x32_bf16 v[36:39], v[242:245], v[152:155], v[36:39]
	v_mfma_f32_16x16x32_bf16 v[44:47], v[242:245], v[156:159], v[44:47]
	ds_read_b128 v[242:245], v162 offset:6144
	s_waitcnt lgkmcnt(3)
	v_mfma_f32_16x16x32_bf16 v[80:83], v[196:199], v[144:147], v[80:83]
	v_mfma_f32_16x16x32_bf16 v[88:91], v[196:199], v[148:151], v[88:91]
	v_mfma_f32_16x16x32_bf16 v[16:19], v[196:199], v[152:155], v[16:19]
	v_mfma_f32_16x16x32_bf16 v[24:27], v[196:199], v[156:159], v[24:27]
	s_waitcnt lgkmcnt(2)
	v_mfma_f32_16x16x32_bf16 v[84:87], v[200:203], v[144:147], v[84:87]
	v_mfma_f32_16x16x32_bf16 v[92:95], v[200:203], v[148:151], v[92:95]
	v_mfma_f32_16x16x32_bf16 v[20:23], v[200:203], v[152:155], v[20:23]
	v_mfma_f32_16x16x32_bf16 v[28:31], v[200:203], v[156:159], v[28:31]
	s_waitcnt lgkmcnt(1)
	v_mfma_f32_16x16x32_bf16 v[64:67], v[204:207], v[144:147], v[64:67]
	v_mfma_f32_16x16x32_bf16 v[72:75], v[204:207], v[148:151], v[72:75]
	v_mfma_f32_16x16x32_bf16 v[0:3], v[204:207], v[152:155], v[0:3]
	v_mfma_f32_16x16x32_bf16 v[8:11], v[204:207], v[156:159], v[8:11]
	s_waitcnt lgkmcnt(0)
	v_mfma_f32_16x16x32_bf16 v[68:71], v[242:245], v[144:147], v[68:71]
	v_mfma_f32_16x16x32_bf16 v[76:79], v[242:245], v[148:151], v[76:79]
	v_mfma_f32_16x16x32_bf16 v[4:7], v[242:245], v[152:155], v[4:7]
	v_mfma_f32_16x16x32_bf16 v[12:15], v[242:245], v[156:159], v[12:15]
	s_barrier
	s_nop 0
	s_nop 7
	s_nop 1
	s_waitcnt vmcnt(0)
	s_waitcnt vmcnt(0)
	v_and_b32_e32 v188, 63, v179
	v_lshrrev_b32_e32 v189, 6, v179
	v_mul_u32_u24_e32 v249, 0x2400, v189
	v_mov_b32_e32 v250, v249
	v_and_b32_e32 v251, 15, v188
	v_mul_u32_u24_e32 v251, 0x110, v251
	v_add_u32_e32 v249, v249, v251
	v_lshrrev_b32_e32 v251, 4, v188
	v_lshl_add_u32 v249, v251, 5, v249
	v_lshrrev_b32_e32 v237, 4, v188
	v_mul_u32_u24_e32 v251, 0x110, v237
	v_add_u32_e32 v250, v250, v251
	v_and_b32_e32 v251, 15, v188
	v_lshlrev_b32_e32 v251, 4, v251
	v_add_u32_e32 v250, v250, v251
	v_lshl_add_u32 v237, v189, 6, v237
	v_lshl_add_u32 v237, v237, 12, v251
	v_add_u32_e32 v238, 16384, v237
	v_add_u32_e32 v239, 32768, v237
	v_add_u32_e32 v240, 49152, v237
	v_add_u32_e32 v241, 65536, v237
	v_add_u32_e32 v242, 81920, v237
	v_add_u32_e32 v243, 98304, v237
	v_add_u32_e32 v248, 114688, v237
	s_lshl_b32 s16, s7, 8
	s_lshl_b32 s18, s6, 9
	s_lshr_b32 s19, s7, 4
	v_readlane_b32 s12, v253, 46
	v_readlane_b32 s13, v253, 47
	v_readlane_b32 s14, v253, 46
	v_readlane_b32 s15, v253, 47
	s_add_i32 s17, s16, 0xffff8000
	s_cmpk_lt_u32 s7, 0x80
	s_cselect_b32 s12, s12, s62
	s_cselect_b32 s13, s13, s63
	s_cselect_b32 s14, s14, s62
	s_cselect_b32 s15, s15, s63
	s_cselect_b32 s19, s19, 8
	s_cselect_b32 s16, s16, s17
	s_mov_b32 s17, 0
	s_lshl_b64 s[16:17], s[16:17], 12
	s_add_u32 s16, s16, s18
	s_addc_u32 s17, s17, 0
	s_add_u32 s12, s12, s16
	s_addc_u32 s13, s13, s17
	s_add_u32 s14, s14, s16
	s_addc_u32 s15, s15, s17
	s_mul_i32 s19, s19, 0x6000
	s_add_u32 s20, s0, s19
	s_addc_u32 s21, s1, 0
	s_add_u32 s20, s20, s18
	s_addc_u32 s21, s21, 0
	global_load_dwordx4 v[244:247], v251, s[20:21]
	global_load_dwordx4 v[160:163], v237, s[12:13]
	global_load_dwordx4 v[164:167], v238, s[12:13]
	global_load_dwordx4 v[168:171], v239, s[12:13]
	global_load_dwordx4 v[172:175], v240, s[12:13]
	global_load_dwordx4 v[196:199], v241, s[12:13]
	global_load_dwordx4 v[200:203], v242, s[12:13]
	global_load_dwordx4 v[204:207], v243, s[12:13]
	global_load_dwordx4 v[184:187], v248, s[12:13]
	ds_write_b128 v249, v[112:115]
	ds_write_b128 v249, v[116:119] offset:16
	ds_write_b128 v249, v[96:99] offset:128
	ds_write_b128 v249, v[100:103] offset:144
	ds_write_b128 v249, v[120:123] offset:4352
	ds_write_b128 v249, v[124:127] offset:4368
	ds_write_b128 v249, v[104:107] offset:4480
	ds_write_b128 v249, v[108:111] offset:4496
	s_waitcnt lgkmcnt(0)
	ds_read_b128 v[128:131], v250
	ds_read_b128 v[132:135], v250 offset:1088
	ds_read_b128 v[136:139], v250 offset:2176
	ds_read_b128 v[140:143], v250 offset:3264
	ds_read_b128 v[144:147], v250 offset:4352
	ds_read_b128 v[148:151], v250 offset:5440
	ds_read_b128 v[152:155], v250 offset:6528
	ds_read_b128 v[156:159], v250 offset:7616
	s_waitcnt vmcnt(7) lgkmcnt(7)
	v_fma_f32 v128, v244, v128, v160
	v_fma_f32 v129, v245, v129, v161
	v_fma_f32 v130, v246, v130, v162
	v_fma_f32 v131, v247, v131, v163
	global_store_dwordx4 v237, v[128:131], s[14:15] sc0 sc1
	s_waitcnt vmcnt(7) lgkmcnt(6)
	v_fma_f32 v132, v244, v132, v164
	v_fma_f32 v133, v245, v133, v165
	v_fma_f32 v134, v246, v134, v166
	v_fma_f32 v135, v247, v135, v167
	global_store_dwordx4 v238, v[132:135], s[14:15] sc0 sc1
	s_waitcnt vmcnt(7) lgkmcnt(5)
	v_fma_f32 v136, v244, v136, v168
	v_fma_f32 v137, v245, v137, v169
	v_fma_f32 v138, v246, v138, v170
	v_fma_f32 v139, v247, v139, v171
	global_store_dwordx4 v239, v[136:139], s[14:15] sc0 sc1
	s_waitcnt vmcnt(7) lgkmcnt(4)
	v_fma_f32 v140, v244, v140, v172
	v_fma_f32 v141, v245, v141, v173
	v_fma_f32 v142, v246, v142, v174
	v_fma_f32 v143, v247, v143, v175
	global_store_dwordx4 v240, v[140:143], s[14:15] sc0 sc1
	s_waitcnt vmcnt(7) lgkmcnt(3)
	v_fma_f32 v144, v244, v144, v196
	v_fma_f32 v145, v245, v145, v197
	v_fma_f32 v146, v246, v146, v198
	v_fma_f32 v147, v247, v147, v199
	global_store_dwordx4 v241, v[144:147], s[14:15] sc0 sc1
	s_waitcnt vmcnt(7) lgkmcnt(2)
	v_fma_f32 v148, v244, v148, v200
	v_fma_f32 v149, v245, v149, v201
	v_fma_f32 v150, v246, v150, v202
	v_fma_f32 v151, v247, v151, v203
	global_store_dwordx4 v242, v[148:151], s[14:15] sc0 sc1
	s_waitcnt vmcnt(7) lgkmcnt(1)
	v_fma_f32 v152, v244, v152, v204
	v_fma_f32 v153, v245, v153, v205
	v_fma_f32 v154, v246, v154, v206
	v_fma_f32 v155, v247, v155, v207
	global_store_dwordx4 v243, v[152:155], s[14:15] sc0 sc1
	s_waitcnt vmcnt(7) lgkmcnt(0)
	v_fma_f32 v156, v244, v156, v184
	v_fma_f32 v157, v245, v157, v185
	v_fma_f32 v158, v246, v158, v186
	v_fma_f32 v159, v247, v159, v187
	global_store_dwordx4 v248, v[156:159], s[14:15] sc0 sc1
	global_load_dwordx4 v[244:247], v251, s[20:21] offset:256
	global_load_dwordx4 v[160:163], v237, s[12:13] offset:256
	global_load_dwordx4 v[164:167], v238, s[12:13] offset:256
	global_load_dwordx4 v[168:171], v239, s[12:13] offset:256
	global_load_dwordx4 v[172:175], v240, s[12:13] offset:256
	global_load_dwordx4 v[196:199], v241, s[12:13] offset:256
	global_load_dwordx4 v[200:203], v242, s[12:13] offset:256
	global_load_dwordx4 v[204:207], v243, s[12:13] offset:256
	global_load_dwordx4 v[184:187], v248, s[12:13] offset:256
	ds_write_b128 v249, v[80:83]
	ds_write_b128 v249, v[84:87] offset:16
	ds_write_b128 v249, v[64:67] offset:128
	ds_write_b128 v249, v[68:71] offset:144
	ds_write_b128 v249, v[88:91] offset:4352
	ds_write_b128 v249, v[92:95] offset:4368
	ds_write_b128 v249, v[72:75] offset:4480
	ds_write_b128 v249, v[76:79] offset:4496
	s_waitcnt lgkmcnt(0)
	ds_read_b128 v[128:131], v250
	ds_read_b128 v[132:135], v250 offset:1088
	ds_read_b128 v[136:139], v250 offset:2176
	ds_read_b128 v[140:143], v250 offset:3264
	ds_read_b128 v[144:147], v250 offset:4352
	ds_read_b128 v[148:151], v250 offset:5440
	ds_read_b128 v[152:155], v250 offset:6528
	ds_read_b128 v[156:159], v250 offset:7616
	s_waitcnt vmcnt(7) lgkmcnt(7)
	v_fma_f32 v128, v244, v128, v160
	v_fma_f32 v129, v245, v129, v161
	v_fma_f32 v130, v246, v130, v162
	v_fma_f32 v131, v247, v131, v163
	global_store_dwordx4 v237, v[128:131], s[14:15] offset:256 sc0 sc1
	s_waitcnt vmcnt(7) lgkmcnt(6)
	v_fma_f32 v132, v244, v132, v164
	v_fma_f32 v133, v245, v133, v165
	v_fma_f32 v134, v246, v134, v166
	v_fma_f32 v135, v247, v135, v167
	global_store_dwordx4 v238, v[132:135], s[14:15] offset:256 sc0 sc1
	s_waitcnt vmcnt(7) lgkmcnt(5)
	v_fma_f32 v136, v244, v136, v168
	v_fma_f32 v137, v245, v137, v169
	v_fma_f32 v138, v246, v138, v170
	v_fma_f32 v139, v247, v139, v171
	global_store_dwordx4 v239, v[136:139], s[14:15] offset:256 sc0 sc1
	s_waitcnt vmcnt(7) lgkmcnt(4)
	v_fma_f32 v140, v244, v140, v172
	v_fma_f32 v141, v245, v141, v173
	v_fma_f32 v142, v246, v142, v174
	v_fma_f32 v143, v247, v143, v175
	global_store_dwordx4 v240, v[140:143], s[14:15] offset:256 sc0 sc1
	s_waitcnt vmcnt(7) lgkmcnt(3)
	v_fma_f32 v144, v244, v144, v196
	v_fma_f32 v145, v245, v145, v197
	v_fma_f32 v146, v246, v146, v198
	v_fma_f32 v147, v247, v147, v199
	global_store_dwordx4 v241, v[144:147], s[14:15] offset:256 sc0 sc1
	s_waitcnt vmcnt(7) lgkmcnt(2)
	v_fma_f32 v148, v244, v148, v200
	v_fma_f32 v149, v245, v149, v201
	v_fma_f32 v150, v246, v150, v202
	v_fma_f32 v151, v247, v151, v203
	global_store_dwordx4 v242, v[148:151], s[14:15] offset:256 sc0 sc1
	s_waitcnt vmcnt(7) lgkmcnt(1)
	v_fma_f32 v152, v244, v152, v204
	v_fma_f32 v153, v245, v153, v205
	v_fma_f32 v154, v246, v154, v206
	v_fma_f32 v155, v247, v155, v207
	global_store_dwordx4 v243, v[152:155], s[14:15] offset:256 sc0 sc1
	s_waitcnt vmcnt(7) lgkmcnt(0)
	v_fma_f32 v156, v244, v156, v184
	v_fma_f32 v157, v245, v157, v185
	v_fma_f32 v158, v246, v158, v186
	v_fma_f32 v159, v247, v159, v187
	global_store_dwordx4 v248, v[156:159], s[14:15] offset:256 sc0 sc1
	s_add_u32 s12, s12, 0x20000
	s_addc_u32 s13, s13, 0
	s_add_u32 s14, s14, 0x20000
	s_addc_u32 s15, s15, 0
	global_load_dwordx4 v[244:247], v251, s[20:21]
	global_load_dwordx4 v[160:163], v237, s[12:13]
	global_load_dwordx4 v[164:167], v238, s[12:13]
	global_load_dwordx4 v[168:171], v239, s[12:13]
	global_load_dwordx4 v[172:175], v240, s[12:13]
	global_load_dwordx4 v[196:199], v241, s[12:13]
	global_load_dwordx4 v[200:203], v242, s[12:13]
	global_load_dwordx4 v[204:207], v243, s[12:13]
	global_load_dwordx4 v[184:187], v248, s[12:13]
	ds_write_b128 v249, v[48:51]
	ds_write_b128 v249, v[52:55] offset:16
	ds_write_b128 v249, v[32:35] offset:128
	ds_write_b128 v249, v[36:39] offset:144
	ds_write_b128 v249, v[56:59] offset:4352
	ds_write_b128 v249, v[60:63] offset:4368
	ds_write_b128 v249, v[40:43] offset:4480
	ds_write_b128 v249, v[44:47] offset:4496
	s_waitcnt lgkmcnt(0)
	ds_read_b128 v[128:131], v250
	ds_read_b128 v[132:135], v250 offset:1088
	ds_read_b128 v[136:139], v250 offset:2176
	ds_read_b128 v[140:143], v250 offset:3264
	ds_read_b128 v[144:147], v250 offset:4352
	ds_read_b128 v[148:151], v250 offset:5440
	ds_read_b128 v[152:155], v250 offset:6528
	ds_read_b128 v[156:159], v250 offset:7616
	s_waitcnt vmcnt(7) lgkmcnt(7)
	v_fma_f32 v128, v244, v128, v160
	v_fma_f32 v129, v245, v129, v161
	v_fma_f32 v130, v246, v130, v162
	v_fma_f32 v131, v247, v131, v163
	global_store_dwordx4 v237, v[128:131], s[14:15] sc0 sc1
	s_waitcnt vmcnt(7) lgkmcnt(6)
	v_fma_f32 v132, v244, v132, v164
	v_fma_f32 v133, v245, v133, v165
	v_fma_f32 v134, v246, v134, v166
	v_fma_f32 v135, v247, v135, v167
	global_store_dwordx4 v238, v[132:135], s[14:15] sc0 sc1
	s_waitcnt vmcnt(7) lgkmcnt(5)
	v_fma_f32 v136, v244, v136, v168
	v_fma_f32 v137, v245, v137, v169
	v_fma_f32 v138, v246, v138, v170
	v_fma_f32 v139, v247, v139, v171
	global_store_dwordx4 v239, v[136:139], s[14:15] sc0 sc1
	s_waitcnt vmcnt(7) lgkmcnt(4)
	v_fma_f32 v140, v244, v140, v172
	v_fma_f32 v141, v245, v141, v173
	v_fma_f32 v142, v246, v142, v174
	v_fma_f32 v143, v247, v143, v175
	global_store_dwordx4 v240, v[140:143], s[14:15] sc0 sc1
	s_waitcnt vmcnt(7) lgkmcnt(3)
	v_fma_f32 v144, v244, v144, v196
	v_fma_f32 v145, v245, v145, v197
	v_fma_f32 v146, v246, v146, v198
	v_fma_f32 v147, v247, v147, v199
	global_store_dwordx4 v241, v[144:147], s[14:15] sc0 sc1
	s_waitcnt vmcnt(7) lgkmcnt(2)
	v_fma_f32 v148, v244, v148, v200
	v_fma_f32 v149, v245, v149, v201
	v_fma_f32 v150, v246, v150, v202
	v_fma_f32 v151, v247, v151, v203
	global_store_dwordx4 v242, v[148:151], s[14:15] sc0 sc1
	s_waitcnt vmcnt(7) lgkmcnt(1)
	v_fma_f32 v152, v244, v152, v204
	v_fma_f32 v153, v245, v153, v205
	v_fma_f32 v154, v246, v154, v206
	v_fma_f32 v155, v247, v155, v207
	global_store_dwordx4 v243, v[152:155], s[14:15] sc0 sc1
	s_waitcnt vmcnt(7) lgkmcnt(0)
	v_fma_f32 v156, v244, v156, v184
	v_fma_f32 v157, v245, v157, v185
	v_fma_f32 v158, v246, v158, v186
	v_fma_f32 v159, v247, v159, v187
	global_store_dwordx4 v248, v[156:159], s[14:15] sc0 sc1
	global_load_dwordx4 v[244:247], v251, s[20:21] offset:256
	global_load_dwordx4 v[160:163], v237, s[12:13] offset:256
	global_load_dwordx4 v[164:167], v238, s[12:13] offset:256
	global_load_dwordx4 v[168:171], v239, s[12:13] offset:256
	global_load_dwordx4 v[172:175], v240, s[12:13] offset:256
	global_load_dwordx4 v[196:199], v241, s[12:13] offset:256
	global_load_dwordx4 v[200:203], v242, s[12:13] offset:256
	global_load_dwordx4 v[204:207], v243, s[12:13] offset:256
	global_load_dwordx4 v[184:187], v248, s[12:13] offset:256
	ds_write_b128 v249, v[16:19]
	ds_write_b128 v249, v[20:23] offset:16
	ds_write_b128 v249, v[0:3] offset:128
	ds_write_b128 v249, v[4:7] offset:144
	ds_write_b128 v249, v[24:27] offset:4352
	ds_write_b128 v249, v[28:31] offset:4368
	ds_write_b128 v249, v[8:11] offset:4480
	ds_write_b128 v249, v[12:15] offset:4496
	s_waitcnt lgkmcnt(0)
	ds_read_b128 v[128:131], v250
	ds_read_b128 v[132:135], v250 offset:1088
	ds_read_b128 v[136:139], v250 offset:2176
	ds_read_b128 v[140:143], v250 offset:3264
	ds_read_b128 v[144:147], v250 offset:4352
	ds_read_b128 v[148:151], v250 offset:5440
	ds_read_b128 v[152:155], v250 offset:6528
	ds_read_b128 v[156:159], v250 offset:7616
	s_waitcnt vmcnt(7) lgkmcnt(7)
	v_fma_f32 v128, v244, v128, v160
	v_fma_f32 v129, v245, v129, v161
	v_fma_f32 v130, v246, v130, v162
	v_fma_f32 v131, v247, v131, v163
	global_store_dwordx4 v237, v[128:131], s[14:15] offset:256 sc0 sc1
	s_waitcnt vmcnt(7) lgkmcnt(6)
	v_fma_f32 v132, v244, v132, v164
	v_fma_f32 v133, v245, v133, v165
	v_fma_f32 v134, v246, v134, v166
	v_fma_f32 v135, v247, v135, v167
	global_store_dwordx4 v238, v[132:135], s[14:15] offset:256 sc0 sc1
	s_waitcnt vmcnt(7) lgkmcnt(5)
	v_fma_f32 v136, v244, v136, v168
	v_fma_f32 v137, v245, v137, v169
	v_fma_f32 v138, v246, v138, v170
	v_fma_f32 v139, v247, v139, v171
	global_store_dwordx4 v239, v[136:139], s[14:15] offset:256 sc0 sc1
	s_waitcnt vmcnt(7) lgkmcnt(4)
	v_fma_f32 v140, v244, v140, v172
	v_fma_f32 v141, v245, v141, v173
	v_fma_f32 v142, v246, v142, v174
	v_fma_f32 v143, v247, v143, v175
	global_store_dwordx4 v240, v[140:143], s[14:15] offset:256 sc0 sc1
	s_waitcnt vmcnt(7) lgkmcnt(3)
	v_fma_f32 v144, v244, v144, v196
	v_fma_f32 v145, v245, v145, v197
	v_fma_f32 v146, v246, v146, v198
	v_fma_f32 v147, v247, v147, v199
	global_store_dwordx4 v241, v[144:147], s[14:15] offset:256 sc0 sc1
	s_waitcnt vmcnt(7) lgkmcnt(2)
	v_fma_f32 v148, v244, v148, v200
	v_fma_f32 v149, v245, v149, v201
	v_fma_f32 v150, v246, v150, v202
	v_fma_f32 v151, v247, v151, v203
	global_store_dwordx4 v242, v[148:151], s[14:15] offset:256 sc0 sc1
	s_waitcnt vmcnt(7) lgkmcnt(1)
	v_fma_f32 v152, v244, v152, v204
	v_fma_f32 v153, v245, v153, v205
	v_fma_f32 v154, v246, v154, v206
	v_fma_f32 v155, v247, v155, v207
	global_store_dwordx4 v243, v[152:155], s[14:15] offset:256 sc0 sc1
	s_waitcnt vmcnt(7) lgkmcnt(0)
	v_fma_f32 v156, v244, v156, v184
	v_fma_f32 v157, v245, v157, v185
	v_fma_f32 v158, v246, v158, v186
	v_fma_f32 v159, v247, v159, v187
	global_store_dwordx4 v248, v[156:159], s[14:15] offset:256 sc0 sc1
	s_waitcnt lgkmcnt(0)
	v_readlane_b32 s16, v254, 11
	s_andn2_b32 s17, s26, 63
	s_add_i32 s2, s2, s16
	s_cmp_lt_i32 s2, s17
	s_cbranch_scc0 .Lhx_down_left
	s_barrier
	s_branch .LBB0_1086
